# GEMM epilogues of the two wave halves run concurrently (one extra barrier per half per unit)
# speedup vs baseline: 1.0413x; 1.0151x over previous
.LBB0_174:
	v_lshrrev_b32_e32 v18, 1, v15
	s_add_u32 s46, s9, 0x19c00000
	v_and_b32_e32 v18, 24, v18
	s_addc_u32 s47, s10, 0
	v_and_b32_e32 v16, 15, v15
	s_lshl_b32 s17, s1, 6
	v_lshlrev_b32_e32 v19, 1, v18
	v_lshlrev_b32_e32 v15, 2, v15
	s_and_b32 s6, s0, 3
	v_or_b32_e32 v17, s17, v16
	v_lshl_or_b32 v16, v16, 6, v19
	s_lshl_b32 s0, s1, 13
	v_and_b32_e32 v15, 32, v15
	s_add_i32 m0, s73, 0x18000
	v_lshl_add_u64 v[8:9], v[8:9], 0, s[24:25]
	v_bitop3_b32 v19, v16, s0, v15 bitop3:0xde
	s_lshl_b32 s0, s6, 12
	s_waitcnt vmcnt(4)
	s_barrier
	global_load_lds_dwordx4 v[8:9], off
	v_lshl_add_u64 v[6:7], v[6:7], 0, s[24:25]
	s_add_i32 m0, s73, 0x1a000
	s_add_i32 s18, s73, 0x8000
	s_add_i32 s19, s73, 0xa000
	v_bitop3_b32 v155, v16, s0, v15 bitop3:0xde
	global_load_lds_dwordx4 v[6:7], off
	v_lshl_add_u64 v[4:5], v[4:5], 0, s[24:25]
	s_mov_b32 m0, s18
	s_add_u32 s0, s62, 0x40080
	global_load_lds_dwordx4 v[4:5], off
	v_lshl_add_u64 v[2:3], v[2:3], 0, s[24:25]
	s_mov_b32 m0, s19
	s_addc_u32 s1, s63, 0
	global_load_lds_dwordx4 v[2:3], off
	s_add_i32 m0, s73, 0x1c000
	v_lshl_add_u64 v[2:3], s[0:1], 0, v[146:147]
	global_load_lds_dwordx4 v[2:3], off
	v_lshl_add_u64 v[2:3], s[0:1], 0, v[148:149]
	s_add_i32 m0, s73, 0x1e000
	v_add_u32_e32 v245, 0x80, v17
	global_load_lds_dwordx4 v[2:3], off
	v_lshlrev_b32_e32 v2, 8, v17
	v_and_b32_e32 v244, 0xcf00, v2
	v_lshlrev_b32_e32 v2, 8, v245
	v_add_u32_e32 v247, 0x90, v17
	v_and_b32_e32 v246, 0xcf00, v2
	v_lshlrev_b32_e32 v2, 8, v247
	v_add_u32_e32 v249, 0xa0, v17
	v_and_b32_e32 v248, 0xdf00, v2
	v_lshlrev_b32_e32 v2, 8, v249
	v_add_u32_e32 v251, 0xb0, v17
	v_and_b32_e32 v250, 0xef00, v2
	v_lshlrev_b32_e32 v2, 8, v251
	v_and_b32_e32 v252, 0xff00, v2
	v_lshlrev_b32_e32 v2, 14, v0
	v_and_b32_e32 v2, 0xffff8000, v2
	v_lshl_add_u32 v2, v10, 11, v2
	v_and_b32_e32 v0, 1, v0
	v_lshl_or_b32 v0, v0, 6, v2
	v_lshl_add_u32 v150, v11, 1, v0
	v_lshlrev_b32_e32 v0, 14, v12
	v_and_b32_e32 v0, 0xffff8000, v0
	s_waitcnt vmcnt(6)
	v_lshl_add_u32 v0, v13, 11, v0
	v_and_b32_e32 v2, 1, v12
	s_add_i32 s0, 0, 0x20000
	v_lshl_or_b32 v0, v2, 6, v0
	v_lshl_add_u32 v179, v18, 2, s0
	s_ashr_i32 s20, s48, 31
	v_lshl_or_b32 v253, s6, 6, v18
	v_mov_b32_e32 v151, v1
	v_lshl_add_u32 v152, v14, 1, v0
	v_mov_b32_e32 v153, v1
	s_mov_b32 s21, 0
	v_add_u32_e32 v231, 0, v19
	s_barrier
	s_branch .LBB0_176
	s_nop 0
	s_nop 0
	s_nop 0
	s_nop 0
	s_nop 0
	s_nop 0
	s_nop 0
	s_nop 0
	s_nop 0
	s_nop 0
	s_nop 0
	s_nop 0
	s_nop 0
.LBB0_175:
	s_and_b64 vcc, exec, s[36:37]
	s_mov_b32 s72, s68
	s_mov_b32 s38, s0
	s_mov_b64 s[62:63], s[88:89]
	s_mov_b64 s[2:3], s[84:85]
	global_store_dwordx4 v[156:157], v[130:133], off offset:64 nt
	s_cmpk_gt_u32 s8, 0xff
	s_cbranch_scc0 .Lepi1_proj
	s_barrier
.Lepi1_proj:
	s_cbranch_vccnz .LBB0_272

.LBB0_179:
	s_add_u32 s6, s2, 0xfffc0080
	s_addc_u32 s7, s3, -1
	s_add_i32 s33, 0, 0x10000
	v_add_u32_e32 v0, s33, v155
	ds_read_b128 v[130:133], v0
	ds_read_b128 v[134:137], v0 offset:1024
	ds_read_b128 v[138:141], v0 offset:2048
	ds_read_b128 v[142:145], v0 offset:3072
	s_cmp_eq_u32 vcc_hi, 12
	s_cselect_b32 s91, s1, s7
	s_cselect_b32 s90, s22, s6
	s_cselect_b32 s63, s23, vcc_lo
	s_cselect_b32 s62, s39, s69
	v_lshl_add_u64 v[176:177], s[2:3], 0, v[150:151]
	s_add_i32 m0, s73, 0xc000
	ds_read_b128 v[156:159], v231
	ds_read_b128 v[160:163], v231 offset:1024
	ds_read_b128 v[164:167], v231 offset:2048
	ds_read_b128 v[168:171], v231 offset:3072
	ds_read_b128 v[172:175], v231 offset:4096
	ds_read_b128 v[184:187], v231 offset:5120
	ds_read_b128 v[188:191], v231 offset:6144
	ds_read_b128 v[192:195], v231 offset:7168
	global_load_lds_dwordx4 v[176:177], off
	v_lshl_add_u64 v[176:177], s[2:3], 0, v[152:153]
	s_add_i32 m0, s73, 0xe000
	s_nop 0
	global_load_lds_dwordx4 v[176:177], off
	s_waitcnt lgkmcnt(8)
	s_barrier
	s_waitcnt lgkmcnt(0)
	s_waitcnt lgkmcnt(0)
	v_mfma_f32_16x16x32_bf16 v[126:129], v[130:133], v[156:159], v[126:129]
	v_mfma_f32_16x16x32_bf16 v[122:125], v[138:141], v[156:159], v[122:125]
	v_mfma_f32_16x16x32_bf16 v[110:113], v[130:133], v[164:167], v[110:113]
	v_mfma_f32_16x16x32_bf16 v[106:109], v[138:141], v[164:167], v[106:109]
	v_mfma_f32_16x16x32_bf16 v[94:97], v[130:133], v[172:175], v[94:97]
	v_mfma_f32_16x16x32_bf16 v[90:93], v[138:141], v[172:175], v[90:93]
	v_mfma_f32_16x16x32_bf16 v[78:81], v[130:133], v[188:191], v[78:81]
	v_mfma_f32_16x16x32_bf16 v[74:77], v[138:141], v[188:191], v[74:77]
	v_mfma_f32_16x16x32_bf16 v[126:129], v[134:137], v[160:163], v[126:129]
	v_mfma_f32_16x16x32_bf16 v[122:125], v[142:145], v[160:163], v[122:125]
	v_mfma_f32_16x16x32_bf16 v[110:113], v[134:137], v[168:171], v[110:113]
	v_mfma_f32_16x16x32_bf16 v[106:109], v[142:145], v[168:171], v[106:109]
	v_mfma_f32_16x16x32_bf16 v[94:97], v[134:137], v[184:187], v[94:97]
	v_mfma_f32_16x16x32_bf16 v[90:93], v[142:145], v[184:187], v[90:93]
	v_mfma_f32_16x16x32_bf16 v[78:81], v[134:137], v[192:195], v[78:81]
	v_mfma_f32_16x16x32_bf16 v[74:77], v[142:145], v[192:195], v[74:77]
	s_barrier
	s_add_i32 s94, 0, 0x14000
	s_add_i32 s6, s33, s11
	v_add_u32_e32 v0, s94, v155
	v_lshl_add_u64 v[176:177], s[62:63], 0, v[146:147]
	s_mov_b32 m0, s6
	ds_read_b128 v[196:199], v0
	ds_read_b128 v[200:203], v0 offset:1024
	ds_read_b128 v[204:207], v0 offset:2048
	ds_read_b128 v[208:211], v0 offset:3072
	global_load_lds_dwordx4 v[176:177], off
	v_lshl_add_u64 v[180:181], s[62:63], 0, v[148:149]
	s_add_i32 m0, s6, 0x2000
	s_nop 0
	global_load_lds_dwordx4 v[180:181], off
	s_barrier
	s_waitcnt lgkmcnt(0)
	s_waitcnt lgkmcnt(0)
	v_mfma_f32_16x16x32_bf16 v[118:121], v[196:199], v[156:159], v[118:121]
	v_mfma_f32_16x16x32_bf16 v[114:117], v[204:207], v[156:159], v[114:117]
	v_mfma_f32_16x16x32_bf16 v[102:105], v[196:199], v[164:167], v[102:105]
	v_mfma_f32_16x16x32_bf16 v[98:101], v[204:207], v[164:167], v[98:101]
	v_mfma_f32_16x16x32_bf16 v[86:89], v[196:199], v[172:175], v[86:89]
	v_mfma_f32_16x16x32_bf16 v[82:85], v[204:207], v[172:175], v[82:85]
	v_mfma_f32_16x16x32_bf16 v[70:73], v[196:199], v[188:191], v[70:73]
	v_mfma_f32_16x16x32_bf16 v[66:69], v[204:207], v[188:191], v[66:69]
	v_mfma_f32_16x16x32_bf16 v[118:121], v[200:203], v[160:163], v[118:121]
	v_mfma_f32_16x16x32_bf16 v[114:117], v[208:211], v[160:163], v[114:117]
	v_mfma_f32_16x16x32_bf16 v[102:105], v[200:203], v[168:171], v[102:105]
	v_mfma_f32_16x16x32_bf16 v[98:101], v[208:211], v[168:171], v[98:101]
	v_mfma_f32_16x16x32_bf16 v[86:89], v[200:203], v[184:187], v[86:89]
	v_mfma_f32_16x16x32_bf16 v[82:85], v[208:211], v[184:187], v[82:85]
	v_mfma_f32_16x16x32_bf16 v[70:73], v[200:203], v[192:195], v[70:73]
	v_mfma_f32_16x16x32_bf16 v[66:69], v[208:211], v[192:195], v[66:69]
	s_mov_b32 m0, s73
	v_lshl_add_u64 v[212:213], s[90:91], 0, v[146:147]
	s_barrier
	ds_read_b128 v[156:159], v231 offset:16384
	ds_read_b128 v[160:163], v231 offset:17408
	ds_read_b128 v[164:167], v231 offset:18432
	ds_read_b128 v[168:171], v231 offset:19456
	ds_read_b128 v[172:175], v231 offset:20480
	ds_read_b128 v[184:187], v231 offset:21504
	ds_read_b128 v[188:191], v231 offset:22528
	ds_read_b128 v[192:195], v231 offset:23552
	global_load_lds_dwordx4 v[212:213], off
	v_lshl_add_u64 v[214:215], s[90:91], 0, v[148:149]
	s_mov_b32 m0, s14
	s_nop 0
	global_load_lds_dwordx4 v[214:215], off
	s_barrier
	s_waitcnt lgkmcnt(0)
	s_waitcnt lgkmcnt(0)
	v_mfma_f32_16x16x32_bf16 v[62:65], v[130:133], v[156:159], v[62:65]
	v_mfma_f32_16x16x32_bf16 v[58:61], v[138:141], v[156:159], v[58:61]
	v_mfma_f32_16x16x32_bf16 v[46:49], v[130:133], v[164:167], v[46:49]
	v_mfma_f32_16x16x32_bf16 v[42:45], v[138:141], v[164:167], v[42:45]
	v_mfma_f32_16x16x32_bf16 v[30:33], v[130:133], v[172:175], v[30:33]
	v_mfma_f32_16x16x32_bf16 v[26:29], v[138:141], v[172:175], v[26:29]
	v_mfma_f32_16x16x32_bf16 v[14:17], v[130:133], v[188:191], v[14:17]
	v_mfma_f32_16x16x32_bf16 v[10:13], v[138:141], v[188:191], v[10:13]
	v_mfma_f32_16x16x32_bf16 v[62:65], v[134:137], v[160:163], v[62:65]
	v_mfma_f32_16x16x32_bf16 v[58:61], v[142:145], v[160:163], v[58:61]
	v_mfma_f32_16x16x32_bf16 v[46:49], v[134:137], v[168:171], v[46:49]
	v_mfma_f32_16x16x32_bf16 v[42:45], v[142:145], v[168:171], v[42:45]
	v_mfma_f32_16x16x32_bf16 v[30:33], v[134:137], v[184:187], v[30:33]
	v_mfma_f32_16x16x32_bf16 v[26:29], v[142:145], v[184:187], v[26:29]
	v_mfma_f32_16x16x32_bf16 v[14:17], v[134:137], v[192:195], v[14:17]
	v_mfma_f32_16x16x32_bf16 v[10:13], v[142:145], v[192:195], v[10:13]
	s_barrier
	s_add_u32 s6, s62, 0x40000
	s_addc_u32 s7, s63, 0
	s_add_i32 s33, s94, s11
	v_lshl_add_u64 v[130:131], s[6:7], 0, v[146:147]
	s_mov_b32 m0, s33
	s_nop 0
	global_load_lds_dwordx4 v[130:131], off
	v_lshl_add_u64 v[130:131], s[6:7], 0, v[148:149]
	s_add_i32 m0, s33, 0x2000
	s_nop 0
	global_load_lds_dwordx4 v[130:131], off
	s_waitcnt vmcnt(6)
	s_barrier
	v_mfma_f32_16x16x32_bf16 v[54:57], v[196:199], v[156:159], v[54:57]
	v_mfma_f32_16x16x32_bf16 v[50:53], v[204:207], v[156:159], v[50:53]
	v_mfma_f32_16x16x32_bf16 v[38:41], v[196:199], v[164:167], v[38:41]
	v_mfma_f32_16x16x32_bf16 v[34:37], v[204:207], v[164:167], v[34:37]
	v_mfma_f32_16x16x32_bf16 v[22:25], v[196:199], v[172:175], v[22:25]
	v_mfma_f32_16x16x32_bf16 v[18:21], v[204:207], v[172:175], v[18:21]
	v_mfma_f32_16x16x32_bf16 v[6:9], v[196:199], v[188:191], v[6:9]
	v_mfma_f32_16x16x32_bf16 v[2:5], v[204:207], v[188:191], v[2:5]
	v_mfma_f32_16x16x32_bf16 v[54:57], v[200:203], v[160:163], v[54:57]
	v_mfma_f32_16x16x32_bf16 v[50:53], v[208:211], v[160:163], v[50:53]
	v_mfma_f32_16x16x32_bf16 v[38:41], v[200:203], v[168:171], v[38:41]
	v_mfma_f32_16x16x32_bf16 v[34:37], v[208:211], v[168:171], v[34:37]
	v_mfma_f32_16x16x32_bf16 v[22:25], v[200:203], v[184:187], v[22:25]
	v_mfma_f32_16x16x32_bf16 v[18:21], v[208:211], v[184:187], v[18:21]
	v_mfma_f32_16x16x32_bf16 v[6:9], v[200:203], v[192:195], v[6:9]
	v_mfma_f32_16x16x32_bf16 v[2:5], v[208:211], v[192:195], v[2:5]
	s_add_i32 s33, 0, 0x18000
	v_add_u32_e32 v0, s33, v155
	s_barrier
	ds_read_b128 v[130:133], v0
	ds_read_b128 v[134:137], v0 offset:1024
	ds_read_b128 v[138:141], v0 offset:2048
	ds_read_b128 v[142:145], v0 offset:3072
	s_add_u32 s6, s90, 0x40000
	s_addc_u32 s7, s91, 0
	s_mov_b32 m0, s15
	v_lshl_add_u64 v[196:197], s[6:7], 0, v[146:147]
	ds_read_b128 v[156:159], v231 offset:32768
	ds_read_b128 v[160:163], v231 offset:33792
	ds_read_b128 v[164:167], v231 offset:34816
	ds_read_b128 v[168:171], v231 offset:35840
	ds_read_b128 v[172:175], v231 offset:36864
	ds_read_b128 v[184:187], v231 offset:37888
	ds_read_b128 v[188:191], v231 offset:38912
	ds_read_b128 v[192:195], v231 offset:39936
	global_load_lds_dwordx4 v[196:197], off
	v_lshl_add_u64 v[196:197], s[6:7], 0, v[148:149]
	s_mov_b32 m0, s16
	s_nop 0
	global_load_lds_dwordx4 v[196:197], off
	s_waitcnt lgkmcnt(8)
	s_barrier
	s_waitcnt lgkmcnt(0)
	s_waitcnt lgkmcnt(0)
	v_mfma_f32_16x16x32_bf16 v[126:129], v[130:133], v[156:159], v[126:129]
	v_mfma_f32_16x16x32_bf16 v[122:125], v[138:141], v[156:159], v[122:125]
	v_mfma_f32_16x16x32_bf16 v[110:113], v[130:133], v[164:167], v[110:113]
	v_mfma_f32_16x16x32_bf16 v[106:109], v[138:141], v[164:167], v[106:109]
	v_mfma_f32_16x16x32_bf16 v[94:97], v[130:133], v[172:175], v[94:97]
	v_mfma_f32_16x16x32_bf16 v[90:93], v[138:141], v[172:175], v[90:93]
	v_mfma_f32_16x16x32_bf16 v[78:81], v[130:133], v[188:191], v[78:81]
	v_mfma_f32_16x16x32_bf16 v[74:77], v[138:141], v[188:191], v[74:77]
	v_mfma_f32_16x16x32_bf16 v[126:129], v[134:137], v[160:163], v[126:129]
	v_mfma_f32_16x16x32_bf16 v[122:125], v[142:145], v[160:163], v[122:125]
	v_mfma_f32_16x16x32_bf16 v[110:113], v[134:137], v[168:171], v[110:113]
	v_mfma_f32_16x16x32_bf16 v[106:109], v[142:145], v[168:171], v[106:109]
	v_mfma_f32_16x16x32_bf16 v[94:97], v[134:137], v[184:187], v[94:97]
	v_mfma_f32_16x16x32_bf16 v[90:93], v[142:145], v[184:187], v[90:93]
	v_mfma_f32_16x16x32_bf16 v[78:81], v[134:137], v[192:195], v[78:81]
	v_mfma_f32_16x16x32_bf16 v[74:77], v[142:145], v[192:195], v[74:77]
	s_barrier
	s_add_i32 s90, 0, 0x1c000
	s_add_i32 s6, s33, s11
	v_add_u32_e32 v0, s90, v155
	v_lshl_add_u64 v[176:177], v[176:177], 0, s[24:25]
	s_mov_b32 m0, s6
	ds_read_b128 v[196:199], v0
	ds_read_b128 v[200:203], v0 offset:1024
	ds_read_b128 v[204:207], v0 offset:2048
	ds_read_b128 v[208:211], v0 offset:3072
	global_load_lds_dwordx4 v[176:177], off
	v_lshl_add_u64 v[176:177], v[180:181], 0, s[24:25]
	s_add_i32 m0, s6, 0x2000
	s_nop 0
	global_load_lds_dwordx4 v[176:177], off
	s_barrier
	s_waitcnt lgkmcnt(0)
	s_waitcnt lgkmcnt(0)
	v_mfma_f32_16x16x32_bf16 v[118:121], v[196:199], v[156:159], v[118:121]
	v_mfma_f32_16x16x32_bf16 v[114:117], v[204:207], v[156:159], v[114:117]
	v_mfma_f32_16x16x32_bf16 v[102:105], v[196:199], v[164:167], v[102:105]
	v_mfma_f32_16x16x32_bf16 v[98:101], v[204:207], v[164:167], v[98:101]
	v_mfma_f32_16x16x32_bf16 v[86:89], v[196:199], v[172:175], v[86:89]
	v_mfma_f32_16x16x32_bf16 v[82:85], v[204:207], v[172:175], v[82:85]
	v_mfma_f32_16x16x32_bf16 v[70:73], v[196:199], v[188:191], v[70:73]
	v_mfma_f32_16x16x32_bf16 v[66:69], v[204:207], v[188:191], v[66:69]
	v_mfma_f32_16x16x32_bf16 v[118:121], v[200:203], v[160:163], v[118:121]
	v_mfma_f32_16x16x32_bf16 v[114:117], v[208:211], v[160:163], v[114:117]
	v_mfma_f32_16x16x32_bf16 v[102:105], v[200:203], v[168:171], v[102:105]
	v_mfma_f32_16x16x32_bf16 v[98:101], v[208:211], v[168:171], v[98:101]
	v_mfma_f32_16x16x32_bf16 v[86:89], v[200:203], v[184:187], v[86:89]
	v_mfma_f32_16x16x32_bf16 v[82:85], v[208:211], v[184:187], v[82:85]
	v_mfma_f32_16x16x32_bf16 v[70:73], v[200:203], v[192:195], v[70:73]
	v_mfma_f32_16x16x32_bf16 v[66:69], v[208:211], v[192:195], v[66:69]
	s_mov_b32 m0, s18
	v_lshl_add_u64 v[176:177], v[212:213], 0, s[24:25]
	s_barrier
	ds_read_b128 v[156:159], v231 offset:49152
	ds_read_b128 v[160:163], v231 offset:50176
	ds_read_b128 v[164:167], v231 offset:51200
	ds_read_b128 v[168:171], v231 offset:52224
	ds_read_b128 v[172:175], v231 offset:53248
	ds_read_b128 v[184:187], v231 offset:54272
	ds_read_b128 v[188:191], v231 offset:55296
	ds_read_b128 v[192:195], v231 offset:56320
	global_load_lds_dwordx4 v[176:177], off
	v_lshl_add_u64 v[176:177], v[214:215], 0, s[24:25]
	s_mov_b32 m0, s19
	s_nop 0
	global_load_lds_dwordx4 v[176:177], off
	s_barrier
	s_waitcnt lgkmcnt(0)
	s_waitcnt lgkmcnt(0)
	v_mfma_f32_16x16x32_bf16 v[62:65], v[130:133], v[156:159], v[62:65]
	v_mfma_f32_16x16x32_bf16 v[58:61], v[138:141], v[156:159], v[58:61]
	v_mfma_f32_16x16x32_bf16 v[46:49], v[130:133], v[164:167], v[46:49]
	v_mfma_f32_16x16x32_bf16 v[42:45], v[138:141], v[164:167], v[42:45]
	v_mfma_f32_16x16x32_bf16 v[30:33], v[130:133], v[172:175], v[30:33]
	v_mfma_f32_16x16x32_bf16 v[26:29], v[138:141], v[172:175], v[26:29]
	v_mfma_f32_16x16x32_bf16 v[14:17], v[130:133], v[188:191], v[14:17]
	v_mfma_f32_16x16x32_bf16 v[10:13], v[138:141], v[188:191], v[10:13]
	v_mfma_f32_16x16x32_bf16 v[62:65], v[134:137], v[160:163], v[62:65]
	v_mfma_f32_16x16x32_bf16 v[58:61], v[142:145], v[160:163], v[58:61]
	v_mfma_f32_16x16x32_bf16 v[46:49], v[134:137], v[168:171], v[46:49]
	v_mfma_f32_16x16x32_bf16 v[42:45], v[142:145], v[168:171], v[42:45]
	v_mfma_f32_16x16x32_bf16 v[30:33], v[134:137], v[184:187], v[30:33]
	v_mfma_f32_16x16x32_bf16 v[26:29], v[142:145], v[184:187], v[26:29]
	v_mfma_f32_16x16x32_bf16 v[14:17], v[134:137], v[192:195], v[14:17]
	v_mfma_f32_16x16x32_bf16 v[10:13], v[142:145], v[192:195], v[10:13]
	s_barrier
	s_add_u32 s6, s62, 0x40080
	s_addc_u32 s7, s63, 0
	s_add_i32 s33, s90, s11
	v_lshl_add_u64 v[130:131], s[6:7], 0, v[146:147]
	s_mov_b32 m0, s33
	s_nop 0
	global_load_lds_dwordx4 v[130:131], off
	v_lshl_add_u64 v[130:131], s[6:7], 0, v[148:149]
	s_add_i32 m0, s33, 0x2000
	s_nop 0
	global_load_lds_dwordx4 v[130:131], off
	s_waitcnt vmcnt(6)
	s_barrier
	v_mfma_f32_16x16x32_bf16 v[54:57], v[196:199], v[156:159], v[54:57]
	v_mfma_f32_16x16x32_bf16 v[50:53], v[204:207], v[156:159], v[50:53]
	v_mfma_f32_16x16x32_bf16 v[38:41], v[196:199], v[164:167], v[38:41]
	v_mfma_f32_16x16x32_bf16 v[34:37], v[204:207], v[164:167], v[34:37]
	v_mfma_f32_16x16x32_bf16 v[22:25], v[196:199], v[172:175], v[22:25]
	v_mfma_f32_16x16x32_bf16 v[18:21], v[204:207], v[172:175], v[18:21]
	v_mfma_f32_16x16x32_bf16 v[6:9], v[196:199], v[188:191], v[6:9]
	v_mfma_f32_16x16x32_bf16 v[2:5], v[204:207], v[188:191], v[2:5]
	v_mfma_f32_16x16x32_bf16 v[54:57], v[200:203], v[160:163], v[54:57]
	v_mfma_f32_16x16x32_bf16 v[50:53], v[208:211], v[160:163], v[50:53]
	v_mfma_f32_16x16x32_bf16 v[38:41], v[200:203], v[168:171], v[38:41]
	v_mfma_f32_16x16x32_bf16 v[34:37], v[208:211], v[168:171], v[34:37]
	v_mfma_f32_16x16x32_bf16 v[22:25], v[200:203], v[184:187], v[22:25]
	v_mfma_f32_16x16x32_bf16 v[18:21], v[208:211], v[184:187], v[18:21]
	v_mfma_f32_16x16x32_bf16 v[6:9], v[200:203], v[192:195], v[6:9]
	v_mfma_f32_16x16x32_bf16 v[2:5], v[208:211], v[192:195], v[2:5]
	s_add_i32 vcc_hi, vcc_hi, 2
	s_add_u32 s2, s2, 0x100
	s_addc_u32 s3, s3, 0
	s_add_u32 s69, s69, 0x100
	s_addc_u32 vcc_lo, vcc_lo, 0
	s_cmp_gt_u32 vcc_hi, 13
	s_barrier
	s_cbranch_scc0 .LBB0_179
	s_cmpk_gt_u32 s8, 0xff
	s_cbranch_scc1 .Lepi0_proj
	s_barrier
.Lepi0_proj:
	s_cmp_gt_i32 s72, 17
	s_cbranch_scc0 .LBB0_182
	s_and_b32 s1, s72, 0x7ffffffe
	s_cmp_gt_u32 s72, 25
	s_cselect_b32 s2, 3, 0
	s_cmp_lg_u32 s1, 22
	s_cselect_b32 s1, s2, 4
	s_cmp_eq_u32 s72, 19
	s_cselect_b64 vcc, -1, 0
	v_mov_b32_e32 v0, 0x3e000000
	s_and_b64 s[2:3], vcc, exec
	v_cndmask_b32_e32 v154, 1.0, v0, vcc
	s_cselect_b32 s39, 2, s1
	s_movk_i32 s94, 0x2000
	s_mov_b32 s1, 0
	s_cbranch_execz .LBB0_183
	s_branch .LBB0_188

.LBB0_520:
	s_waitcnt vmcnt(0)
	v_lshlrev_b32_e32 v68, 16, v62
	v_and_b32_e32 v69, 0xffff0000, v62
	v_lshlrev_b32_e32 v62, 16, v63
	v_and_b32_e32 v63, 0xffff0000, v63
	v_pk_mul_f32 v[68:69], v[174:175], v[68:69]
	v_lshlrev_b32_e32 v70, 16, v58
	v_and_b32_e32 v71, 0xffff0000, v58
	v_pk_mul_f32 v[62:63], v[174:175], v[62:63]
	v_lshlrev_b32_e32 v58, 16, v59
	v_and_b32_e32 v59, 0xffff0000, v59
	v_pk_fma_f32 v[30:31], v[30:31], v[70:71], v[68:69]
	v_pk_fma_f32 v[32:33], v[32:33], v[58:59], v[62:63]
	v_cvt_pk_bf16_f32 v30, v30, v31
	v_cvt_pk_bf16_f32 v31, v32, v33
	v_lshlrev_b32_e32 v32, 16, v64
	v_and_b32_e32 v33, 0xffff0000, v64
	v_pk_mul_f32 v[32:33], v[174:175], v[32:33]
	v_lshlrev_b32_e32 v58, 16, v60
	v_and_b32_e32 v59, 0xffff0000, v60
	v_pk_fma_f32 v[26:27], v[26:27], v[58:59], v[32:33]
	v_lshlrev_b32_e32 v58, 16, v61
	v_cvt_pk_bf16_f32 v32, v26, v27
	v_lshlrev_b32_e32 v26, 16, v65
	v_and_b32_e32 v27, 0xffff0000, v65
	v_pk_mul_f32 v[26:27], v[174:175], v[26:27]
	v_and_b32_e32 v59, 0xffff0000, v61
	v_pk_fma_f32 v[26:27], v[28:29], v[58:59], v[26:27]
	v_lshlrev_b32_e32 v28, 16, v46
	v_cvt_pk_bf16_f32 v33, v26, v27
	v_lshlrev_b32_e32 v26, 16, v50
	v_and_b32_e32 v27, 0xffff0000, v50
	v_pk_mul_f32 v[26:27], v[174:175], v[26:27]
	v_and_b32_e32 v29, 0xffff0000, v46
	v_pk_fma_f32 v[22:23], v[22:23], v[28:29], v[26:27]
	v_lshlrev_b32_e32 v26, 16, v51
	v_and_b32_e32 v27, 0xffff0000, v51
	v_pk_mul_f32 v[26:27], v[174:175], v[26:27]
	v_lshlrev_b32_e32 v28, 16, v47
	v_and_b32_e32 v29, 0xffff0000, v47
	v_pk_fma_f32 v[24:25], v[24:25], v[28:29], v[26:27]
	v_cvt_pk_bf16_f32 v22, v22, v23
	v_cvt_pk_bf16_f32 v23, v24, v25
	v_lshlrev_b32_e32 v24, 16, v52
	v_and_b32_e32 v25, 0xffff0000, v52
	v_pk_mul_f32 v[24:25], v[174:175], v[24:25]
	v_lshlrev_b32_e32 v26, 16, v48
	v_and_b32_e32 v27, 0xffff0000, v48
	v_add_u32_e32 v66, 0xa0, v170
	v_pk_fma_f32 v[18:19], v[18:19], v[26:27], v[24:25]
	v_ashrrev_i32_e32 v67, 31, v66
	v_cvt_pk_bf16_f32 v24, v18, v19
	v_lshlrev_b32_e32 v18, 16, v53
	v_and_b32_e32 v19, 0xffff0000, v53
	v_lshlrev_b64 v[66:67], 11, v[66:67]
	v_pk_mul_f32 v[18:19], v[174:175], v[18:19]
	v_lshlrev_b32_e32 v26, 16, v49
	v_and_b32_e32 v27, 0xffff0000, v49
	v_lshl_add_u64 v[66:67], s[0:1], 0, v[66:67]
	v_mov_b32_e32 v173, v1
	v_pk_fma_f32 v[18:19], v[20:21], v[26:27], v[18:19]
	v_lshl_add_u64 v[66:67], v[66:67], 0, v[172:173]
	v_cvt_pk_bf16_f32 v25, v18, v19
	v_lshlrev_b32_e32 v20, 16, v54
	v_and_b32_e32 v21, 0xffff0000, v54
	global_store_dwordx4 v[66:67], v[22:25], off offset:64
	v_pk_mul_f32 v[20:21], v[174:175], v[20:21]
	v_add_u32_e32 v18, 0xb0, v170
	v_lshlrev_b32_e32 v22, 16, v42
	v_and_b32_e32 v23, 0xffff0000, v42
	v_pk_fma_f32 v[14:15], v[14:15], v[22:23], v[20:21]
	v_lshlrev_b32_e32 v20, 16, v55
	v_and_b32_e32 v21, 0xffff0000, v55
	v_pk_mul_f32 v[20:21], v[174:175], v[20:21]
	v_lshlrev_b32_e32 v22, 16, v43
	v_and_b32_e32 v23, 0xffff0000, v43
	v_pk_fma_f32 v[16:17], v[16:17], v[22:23], v[20:21]
	v_cvt_pk_bf16_f32 v14, v14, v15
	v_cvt_pk_bf16_f32 v15, v16, v17
	v_lshlrev_b32_e32 v16, 16, v56
	v_and_b32_e32 v17, 0xffff0000, v56
	v_pk_mul_f32 v[16:17], v[174:175], v[16:17]
	v_lshlrev_b32_e32 v20, 16, v44
	v_and_b32_e32 v21, 0xffff0000, v44
	v_pk_fma_f32 v[10:11], v[10:11], v[20:21], v[16:17]
	v_lshlrev_b32_e32 v20, 16, v45
	v_cvt_pk_bf16_f32 v16, v10, v11
	v_lshlrev_b32_e32 v10, 16, v57
	v_and_b32_e32 v11, 0xffff0000, v57
	v_pk_mul_f32 v[10:11], v[174:175], v[10:11]
	v_and_b32_e32 v21, 0xffff0000, v45
	v_pk_fma_f32 v[10:11], v[12:13], v[20:21], v[10:11]
	v_lshlrev_b32_e32 v12, 16, v38
	v_cvt_pk_bf16_f32 v17, v10, v11
	v_lshlrev_b32_e32 v10, 16, v34
	v_and_b32_e32 v11, 0xffff0000, v34
	v_pk_mul_f32 v[10:11], v[174:175], v[10:11]
	v_and_b32_e32 v13, 0xffff0000, v38
	v_pk_fma_f32 v[6:7], v[6:7], v[12:13], v[10:11]
	v_lshlrev_b32_e32 v10, 16, v35
	v_and_b32_e32 v11, 0xffff0000, v35
	v_pk_mul_f32 v[10:11], v[174:175], v[10:11]
	v_lshlrev_b32_e32 v12, 16, v39
	v_and_b32_e32 v13, 0xffff0000, v39
	v_pk_fma_f32 v[8:9], v[8:9], v[12:13], v[10:11]
	v_cvt_pk_bf16_f32 v6, v6, v7
	v_cvt_pk_bf16_f32 v7, v8, v9
	v_lshlrev_b32_e32 v8, 16, v36
	v_and_b32_e32 v9, 0xffff0000, v36
	v_pk_mul_f32 v[8:9], v[174:175], v[8:9]
	v_lshlrev_b32_e32 v10, 16, v40
	v_and_b32_e32 v11, 0xffff0000, v40
	v_pk_fma_f32 v[2:3], v[2:3], v[10:11], v[8:9]
	v_ashrrev_i32_e32 v19, 31, v18
	v_cvt_pk_bf16_f32 v8, v2, v3
	v_lshlrev_b32_e32 v2, 16, v37
	v_and_b32_e32 v3, 0xffff0000, v37
	v_lshlrev_b64 v[18:19], 11, v[18:19]
	v_pk_mul_f32 v[2:3], v[174:175], v[2:3]
	v_lshlrev_b32_e32 v10, 16, v41
	v_and_b32_e32 v11, 0xffff0000, v41
	v_lshl_add_u64 v[18:19], s[0:1], 0, v[18:19]
	v_pk_fma_f32 v[2:3], v[4:5], v[10:11], v[2:3]
	v_lshl_add_u64 v[18:19], v[18:19], 0, v[172:173]
	v_cvt_pk_bf16_f32 v9, v2, v3
	s_and_b64 vcc, exec, s[36:37]
	s_mov_b32 s38, s68
	s_mov_b32 s2, s46
	s_mov_b64 s[90:91], s[88:89]
	s_mov_b64 s[62:63], s[84:85]
	global_store_dwordx4 v[66:67], v[30:33], off
	global_store_dwordx4 v[18:19], v[14:17], off
	global_store_dwordx4 v[18:19], v[6:9], off offset:64
	s_cmpk_gt_u32 s9, 0xff
	s_cbranch_scc0 .Lepi1_branch
	s_barrier

.LBB0_528:
	s_add_u32 s6, s62, 0xfffe0080
	s_addc_u32 s33, s63, -1
	s_add_i32 s72, 0, 0x10000
	v_add_u32_e32 v0, s72, v184
	ds_read_b128 v[130:133], v0
	ds_read_b128 v[134:137], v0 offset:1024
	ds_read_b128 v[138:141], v0 offset:2048
	ds_read_b128 v[142:145], v0 offset:3072
	s_cmp_eq_u32 s69, 4
	s_cselect_b32 vcc_hi, s21, s33
	s_cselect_b32 vcc_lo, s22, s6
	s_cselect_b32 s91, s23, s48
	s_cselect_b32 s90, s39, s47
	v_lshl_add_u64 v[180:181], s[62:63], 0, v[166:167]
	s_add_i32 m0, s3, 0xc000
	ds_read_b128 v[146:149], v201
	ds_read_b128 v[150:153], v201 offset:1024
	ds_read_b128 v[154:157], v201 offset:2048
	ds_read_b128 v[158:161], v201 offset:3072
	ds_read_b128 v[170:173], v201 offset:4096
	ds_read_b128 v[174:177], v201 offset:5120
	ds_read_b128 v[202:205], v201 offset:6144
	ds_read_b128 v[206:209], v201 offset:7168
	global_load_lds_dwordx4 v[180:181], off
	v_lshl_add_u64 v[180:181], s[62:63], 0, v[168:169]
	s_add_i32 m0, s3, 0xe000
	s_nop 0
	global_load_lds_dwordx4 v[180:181], off
	s_waitcnt lgkmcnt(8)
	s_barrier
	s_waitcnt lgkmcnt(0)
	s_waitcnt lgkmcnt(0)
	v_mfma_f32_16x16x32_bf16 v[126:129], v[130:133], v[146:149], v[126:129]
	v_mfma_f32_16x16x32_bf16 v[122:125], v[138:141], v[146:149], v[122:125]
	v_mfma_f32_16x16x32_bf16 v[110:113], v[130:133], v[154:157], v[110:113]
	v_mfma_f32_16x16x32_bf16 v[106:109], v[138:141], v[154:157], v[106:109]
	v_mfma_f32_16x16x32_bf16 v[94:97], v[130:133], v[170:173], v[94:97]
	v_mfma_f32_16x16x32_bf16 v[90:93], v[138:141], v[170:173], v[90:93]
	v_mfma_f32_16x16x32_bf16 v[78:81], v[130:133], v[202:205], v[78:81]
	v_mfma_f32_16x16x32_bf16 v[74:77], v[138:141], v[202:205], v[74:77]
	v_mfma_f32_16x16x32_bf16 v[126:129], v[134:137], v[150:153], v[126:129]
	v_mfma_f32_16x16x32_bf16 v[122:125], v[142:145], v[150:153], v[122:125]
	v_mfma_f32_16x16x32_bf16 v[110:113], v[134:137], v[158:161], v[110:113]
	v_mfma_f32_16x16x32_bf16 v[106:109], v[142:145], v[158:161], v[106:109]
	v_mfma_f32_16x16x32_bf16 v[94:97], v[134:137], v[174:177], v[94:97]
	v_mfma_f32_16x16x32_bf16 v[90:93], v[142:145], v[174:177], v[90:93]
	v_mfma_f32_16x16x32_bf16 v[78:81], v[134:137], v[206:209], v[78:81]
	v_mfma_f32_16x16x32_bf16 v[74:77], v[142:145], v[206:209], v[74:77]
	s_barrier
	s_add_i32 s6, 0, 0x14000
	s_add_i32 s33, s72, s14
	v_add_u32_e32 v0, s6, v184
	v_lshl_add_u64 v[180:181], s[90:91], 0, v[162:163]
	s_mov_b32 m0, s33
	ds_read_b128 v[210:213], v0
	ds_read_b128 v[214:217], v0 offset:1024
	ds_read_b128 v[218:221], v0 offset:2048
	ds_read_b128 v[222:225], v0 offset:3072
	global_load_lds_dwordx4 v[180:181], off
	v_lshl_add_u64 v[226:227], s[90:91], 0, v[164:165]
	s_add_i32 m0, s33, 0x2000
	s_nop 0
	global_load_lds_dwordx4 v[226:227], off
	s_barrier
	s_waitcnt lgkmcnt(0)
	s_waitcnt lgkmcnt(0)
	v_mfma_f32_16x16x32_bf16 v[118:121], v[210:213], v[146:149], v[118:121]
	v_mfma_f32_16x16x32_bf16 v[114:117], v[218:221], v[146:149], v[114:117]
	v_mfma_f32_16x16x32_bf16 v[102:105], v[210:213], v[154:157], v[102:105]
	v_mfma_f32_16x16x32_bf16 v[98:101], v[218:221], v[154:157], v[98:101]
	v_mfma_f32_16x16x32_bf16 v[86:89], v[210:213], v[170:173], v[86:89]
	v_mfma_f32_16x16x32_bf16 v[82:85], v[218:221], v[170:173], v[82:85]
	v_mfma_f32_16x16x32_bf16 v[70:73], v[210:213], v[202:205], v[70:73]
	v_mfma_f32_16x16x32_bf16 v[66:69], v[218:221], v[202:205], v[66:69]
	v_mfma_f32_16x16x32_bf16 v[118:121], v[214:217], v[150:153], v[118:121]
	v_mfma_f32_16x16x32_bf16 v[114:117], v[222:225], v[150:153], v[114:117]
	v_mfma_f32_16x16x32_bf16 v[102:105], v[214:217], v[158:161], v[102:105]
	v_mfma_f32_16x16x32_bf16 v[98:101], v[222:225], v[158:161], v[98:101]
	v_mfma_f32_16x16x32_bf16 v[86:89], v[214:217], v[174:177], v[86:89]
	v_mfma_f32_16x16x32_bf16 v[82:85], v[222:225], v[174:177], v[82:85]
	v_mfma_f32_16x16x32_bf16 v[70:73], v[214:217], v[206:209], v[70:73]
	v_mfma_f32_16x16x32_bf16 v[66:69], v[222:225], v[206:209], v[66:69]
	s_mov_b32 m0, s3
	v_lshl_add_u64 v[240:241], vcc, 0, v[162:163]
	s_barrier
	ds_read_b128 v[146:149], v201 offset:16384
	ds_read_b128 v[150:153], v201 offset:17408
	ds_read_b128 v[154:157], v201 offset:18432
	ds_read_b128 v[158:161], v201 offset:19456
	ds_read_b128 v[170:173], v201 offset:20480
	ds_read_b128 v[174:177], v201 offset:21504
	ds_read_b128 v[202:205], v201 offset:22528
	ds_read_b128 v[206:209], v201 offset:23552
	global_load_lds_dwordx4 v[240:241], off
	v_lshl_add_u64 v[244:245], vcc, 0, v[164:165]
	s_mov_b32 m0, s15
	s_nop 0
	global_load_lds_dwordx4 v[244:245], off
	s_barrier
	s_waitcnt lgkmcnt(0)
	s_waitcnt lgkmcnt(0)
	v_mfma_f32_16x16x32_bf16 v[62:65], v[130:133], v[146:149], v[62:65]
	v_mfma_f32_16x16x32_bf16 v[58:61], v[138:141], v[146:149], v[58:61]
	v_mfma_f32_16x16x32_bf16 v[46:49], v[130:133], v[154:157], v[46:49]
	v_mfma_f32_16x16x32_bf16 v[42:45], v[138:141], v[154:157], v[42:45]
	v_mfma_f32_16x16x32_bf16 v[30:33], v[130:133], v[170:173], v[30:33]
	v_mfma_f32_16x16x32_bf16 v[26:29], v[138:141], v[170:173], v[26:29]
	v_mfma_f32_16x16x32_bf16 v[14:17], v[130:133], v[202:205], v[14:17]
	v_mfma_f32_16x16x32_bf16 v[10:13], v[138:141], v[202:205], v[10:13]
	v_mfma_f32_16x16x32_bf16 v[62:65], v[134:137], v[150:153], v[62:65]
	v_mfma_f32_16x16x32_bf16 v[58:61], v[142:145], v[150:153], v[58:61]
	v_mfma_f32_16x16x32_bf16 v[46:49], v[134:137], v[158:161], v[46:49]
	v_mfma_f32_16x16x32_bf16 v[42:45], v[142:145], v[158:161], v[42:45]
	v_mfma_f32_16x16x32_bf16 v[30:33], v[134:137], v[174:177], v[30:33]
	v_mfma_f32_16x16x32_bf16 v[26:29], v[142:145], v[174:177], v[26:29]
	v_mfma_f32_16x16x32_bf16 v[14:17], v[134:137], v[206:209], v[14:17]
	v_mfma_f32_16x16x32_bf16 v[10:13], v[142:145], v[206:209], v[10:13]
	s_barrier
	s_add_u32 s72, s90, 0x20000
	s_addc_u32 s73, s91, 0
	s_add_i32 s6, s6, s14
	v_lshl_add_u64 v[130:131], s[72:73], 0, v[162:163]
	s_mov_b32 m0, s6
	s_nop 0
	global_load_lds_dwordx4 v[130:131], off
	v_lshl_add_u64 v[130:131], s[72:73], 0, v[164:165]
	s_add_i32 m0, s6, 0x2000
	s_nop 0
	global_load_lds_dwordx4 v[130:131], off
	s_waitcnt vmcnt(6)
	s_barrier
	v_mfma_f32_16x16x32_bf16 v[54:57], v[210:213], v[146:149], v[54:57]
	v_mfma_f32_16x16x32_bf16 v[50:53], v[218:221], v[146:149], v[50:53]
	v_mfma_f32_16x16x32_bf16 v[38:41], v[210:213], v[154:157], v[38:41]
	v_mfma_f32_16x16x32_bf16 v[34:37], v[218:221], v[154:157], v[34:37]
	v_mfma_f32_16x16x32_bf16 v[22:25], v[210:213], v[170:173], v[22:25]
	v_mfma_f32_16x16x32_bf16 v[18:21], v[218:221], v[170:173], v[18:21]
	v_mfma_f32_16x16x32_bf16 v[6:9], v[210:213], v[202:205], v[6:9]
	v_mfma_f32_16x16x32_bf16 v[2:5], v[218:221], v[202:205], v[2:5]
	v_mfma_f32_16x16x32_bf16 v[54:57], v[214:217], v[150:153], v[54:57]
	v_mfma_f32_16x16x32_bf16 v[50:53], v[222:225], v[150:153], v[50:53]
	v_mfma_f32_16x16x32_bf16 v[38:41], v[214:217], v[158:161], v[38:41]
	v_mfma_f32_16x16x32_bf16 v[34:37], v[222:225], v[158:161], v[34:37]
	v_mfma_f32_16x16x32_bf16 v[22:25], v[214:217], v[174:177], v[22:25]
	v_mfma_f32_16x16x32_bf16 v[18:21], v[222:225], v[174:177], v[18:21]
	v_mfma_f32_16x16x32_bf16 v[6:9], v[214:217], v[206:209], v[6:9]
	v_mfma_f32_16x16x32_bf16 v[2:5], v[222:225], v[206:209], v[2:5]
	s_add_i32 s6, 0, 0x18000
	v_add_u32_e32 v0, s6, v184
	s_barrier
	ds_read_b128 v[130:133], v0
	ds_read_b128 v[134:137], v0 offset:1024
	ds_read_b128 v[138:141], v0 offset:2048
	ds_read_b128 v[142:145], v0 offset:3072
	s_add_u32 s72, vcc_lo, 0x20000
	s_addc_u32 s73, vcc_hi, 0
	s_mov_b32 m0, s16
	v_lshl_add_u64 v[210:211], s[72:73], 0, v[162:163]
	ds_read_b128 v[146:149], v201 offset:32768
	ds_read_b128 v[150:153], v201 offset:33792
	ds_read_b128 v[154:157], v201 offset:34816
	ds_read_b128 v[158:161], v201 offset:35840
	ds_read_b128 v[170:173], v201 offset:36864
	ds_read_b128 v[174:177], v201 offset:37888
	ds_read_b128 v[202:205], v201 offset:38912
	ds_read_b128 v[206:209], v201 offset:39936
	global_load_lds_dwordx4 v[210:211], off
	v_lshl_add_u64 v[210:211], s[72:73], 0, v[164:165]
	s_mov_b32 m0, s17
	s_nop 0
	global_load_lds_dwordx4 v[210:211], off
	s_waitcnt lgkmcnt(8)
	s_barrier
	s_waitcnt lgkmcnt(0)
	s_waitcnt lgkmcnt(0)
	v_mfma_f32_16x16x32_bf16 v[126:129], v[130:133], v[146:149], v[126:129]
	v_mfma_f32_16x16x32_bf16 v[122:125], v[138:141], v[146:149], v[122:125]
	v_mfma_f32_16x16x32_bf16 v[110:113], v[130:133], v[154:157], v[110:113]
	v_mfma_f32_16x16x32_bf16 v[106:109], v[138:141], v[154:157], v[106:109]
	v_mfma_f32_16x16x32_bf16 v[94:97], v[130:133], v[170:173], v[94:97]
	v_mfma_f32_16x16x32_bf16 v[90:93], v[138:141], v[170:173], v[90:93]
	v_mfma_f32_16x16x32_bf16 v[78:81], v[130:133], v[202:205], v[78:81]
	v_mfma_f32_16x16x32_bf16 v[74:77], v[138:141], v[202:205], v[74:77]
	v_mfma_f32_16x16x32_bf16 v[126:129], v[134:137], v[150:153], v[126:129]
	v_mfma_f32_16x16x32_bf16 v[122:125], v[142:145], v[150:153], v[122:125]
	v_mfma_f32_16x16x32_bf16 v[110:113], v[134:137], v[158:161], v[110:113]
	v_mfma_f32_16x16x32_bf16 v[106:109], v[142:145], v[158:161], v[106:109]
	v_mfma_f32_16x16x32_bf16 v[94:97], v[134:137], v[174:177], v[94:97]
	v_mfma_f32_16x16x32_bf16 v[90:93], v[142:145], v[174:177], v[90:93]
	v_mfma_f32_16x16x32_bf16 v[78:81], v[134:137], v[206:209], v[78:81]
	v_mfma_f32_16x16x32_bf16 v[74:77], v[142:145], v[206:209], v[74:77]
	s_barrier
	s_add_i32 s33, 0, 0x1c000
	s_add_i32 s6, s6, s14
	v_add_u32_e32 v0, s33, v184
	v_lshl_add_u64 v[180:181], v[180:181], 0, s[24:25]
	s_mov_b32 m0, s6
	ds_read_b128 v[210:213], v0
	ds_read_b128 v[214:217], v0 offset:1024
	ds_read_b128 v[218:221], v0 offset:2048
	ds_read_b128 v[222:225], v0 offset:3072
	global_load_lds_dwordx4 v[180:181], off
	v_lshl_add_u64 v[180:181], v[226:227], 0, s[24:25]
	s_add_i32 m0, s6, 0x2000
	s_nop 0
	global_load_lds_dwordx4 v[180:181], off
	s_barrier
	s_waitcnt lgkmcnt(0)
	s_waitcnt lgkmcnt(0)
	v_mfma_f32_16x16x32_bf16 v[118:121], v[210:213], v[146:149], v[118:121]
	v_mfma_f32_16x16x32_bf16 v[114:117], v[218:221], v[146:149], v[114:117]
	v_mfma_f32_16x16x32_bf16 v[102:105], v[210:213], v[154:157], v[102:105]
	v_mfma_f32_16x16x32_bf16 v[98:101], v[218:221], v[154:157], v[98:101]
	v_mfma_f32_16x16x32_bf16 v[86:89], v[210:213], v[170:173], v[86:89]
	v_mfma_f32_16x16x32_bf16 v[82:85], v[218:221], v[170:173], v[82:85]
	v_mfma_f32_16x16x32_bf16 v[70:73], v[210:213], v[202:205], v[70:73]
	v_mfma_f32_16x16x32_bf16 v[66:69], v[218:221], v[202:205], v[66:69]
	v_mfma_f32_16x16x32_bf16 v[118:121], v[214:217], v[150:153], v[118:121]
	v_mfma_f32_16x16x32_bf16 v[114:117], v[222:225], v[150:153], v[114:117]
	v_mfma_f32_16x16x32_bf16 v[102:105], v[214:217], v[158:161], v[102:105]
	v_mfma_f32_16x16x32_bf16 v[98:101], v[222:225], v[158:161], v[98:101]
	v_mfma_f32_16x16x32_bf16 v[86:89], v[214:217], v[174:177], v[86:89]
	v_mfma_f32_16x16x32_bf16 v[82:85], v[222:225], v[174:177], v[82:85]
	v_mfma_f32_16x16x32_bf16 v[70:73], v[214:217], v[206:209], v[70:73]
	v_mfma_f32_16x16x32_bf16 v[66:69], v[222:225], v[206:209], v[66:69]
	s_mov_b32 m0, s7
	v_lshl_add_u64 v[180:181], v[240:241], 0, s[24:25]
	s_barrier
	ds_read_b128 v[146:149], v201 offset:49152
	ds_read_b128 v[150:153], v201 offset:50176
	ds_read_b128 v[154:157], v201 offset:51200
	ds_read_b128 v[158:161], v201 offset:52224
	ds_read_b128 v[170:173], v201 offset:53248
	ds_read_b128 v[174:177], v201 offset:54272
	ds_read_b128 v[202:205], v201 offset:55296
	ds_read_b128 v[206:209], v201 offset:56320
	global_load_lds_dwordx4 v[180:181], off
	v_lshl_add_u64 v[180:181], v[244:245], 0, s[24:25]
	s_mov_b32 m0, s18
	s_nop 0
	global_load_lds_dwordx4 v[180:181], off
	s_barrier
	s_waitcnt lgkmcnt(0)
	s_waitcnt lgkmcnt(0)
	v_mfma_f32_16x16x32_bf16 v[62:65], v[130:133], v[146:149], v[62:65]
	v_mfma_f32_16x16x32_bf16 v[58:61], v[138:141], v[146:149], v[58:61]
	v_mfma_f32_16x16x32_bf16 v[46:49], v[130:133], v[154:157], v[46:49]
	v_mfma_f32_16x16x32_bf16 v[42:45], v[138:141], v[154:157], v[42:45]
	v_mfma_f32_16x16x32_bf16 v[30:33], v[130:133], v[170:173], v[30:33]
	v_mfma_f32_16x16x32_bf16 v[26:29], v[138:141], v[170:173], v[26:29]
	v_mfma_f32_16x16x32_bf16 v[14:17], v[130:133], v[202:205], v[14:17]
	v_mfma_f32_16x16x32_bf16 v[10:13], v[138:141], v[202:205], v[10:13]
	v_mfma_f32_16x16x32_bf16 v[62:65], v[134:137], v[150:153], v[62:65]
	v_mfma_f32_16x16x32_bf16 v[58:61], v[142:145], v[150:153], v[58:61]
	v_mfma_f32_16x16x32_bf16 v[46:49], v[134:137], v[158:161], v[46:49]
	v_mfma_f32_16x16x32_bf16 v[42:45], v[142:145], v[158:161], v[42:45]
	v_mfma_f32_16x16x32_bf16 v[30:33], v[134:137], v[174:177], v[30:33]
	v_mfma_f32_16x16x32_bf16 v[26:29], v[142:145], v[174:177], v[26:29]
	v_mfma_f32_16x16x32_bf16 v[14:17], v[134:137], v[206:209], v[14:17]
	v_mfma_f32_16x16x32_bf16 v[10:13], v[142:145], v[206:209], v[10:13]
	s_barrier
	s_add_u32 s72, s90, 0x20080
	s_addc_u32 s73, s91, 0
	s_add_i32 s6, s33, s14
	v_lshl_add_u64 v[130:131], s[72:73], 0, v[162:163]
	s_mov_b32 m0, s6
	s_nop 0
	global_load_lds_dwordx4 v[130:131], off
	v_lshl_add_u64 v[130:131], s[72:73], 0, v[164:165]
	s_add_i32 m0, s6, 0x2000
	s_nop 0
	global_load_lds_dwordx4 v[130:131], off
	s_waitcnt vmcnt(6)
	s_barrier
	v_mfma_f32_16x16x32_bf16 v[54:57], v[210:213], v[146:149], v[54:57]
	v_mfma_f32_16x16x32_bf16 v[50:53], v[218:221], v[146:149], v[50:53]
	v_mfma_f32_16x16x32_bf16 v[38:41], v[210:213], v[154:157], v[38:41]
	v_mfma_f32_16x16x32_bf16 v[34:37], v[218:221], v[154:157], v[34:37]
	v_mfma_f32_16x16x32_bf16 v[22:25], v[210:213], v[170:173], v[22:25]
	v_mfma_f32_16x16x32_bf16 v[18:21], v[218:221], v[170:173], v[18:21]
	v_mfma_f32_16x16x32_bf16 v[6:9], v[210:213], v[202:205], v[6:9]
	v_mfma_f32_16x16x32_bf16 v[2:5], v[218:221], v[202:205], v[2:5]
	v_mfma_f32_16x16x32_bf16 v[54:57], v[214:217], v[150:153], v[54:57]
	v_mfma_f32_16x16x32_bf16 v[50:53], v[222:225], v[150:153], v[50:53]
	v_mfma_f32_16x16x32_bf16 v[38:41], v[214:217], v[158:161], v[38:41]
	v_mfma_f32_16x16x32_bf16 v[34:37], v[222:225], v[158:161], v[34:37]
	v_mfma_f32_16x16x32_bf16 v[22:25], v[214:217], v[174:177], v[22:25]
	v_mfma_f32_16x16x32_bf16 v[18:21], v[222:225], v[174:177], v[18:21]
	v_mfma_f32_16x16x32_bf16 v[6:9], v[214:217], v[206:209], v[6:9]
	v_mfma_f32_16x16x32_bf16 v[2:5], v[222:225], v[206:209], v[2:5]
	s_add_i32 s69, s69, 2
	s_add_u32 s62, s62, 0x100
	s_addc_u32 s63, s63, 0
	s_add_u32 s47, s47, 0x100
	s_addc_u32 s48, s48, 0
	s_cmp_gt_u32 s69, 5
	s_barrier
	s_cbranch_scc0 .LBB0_528
	s_cmpk_gt_u32 s9, 0xff
	s_cbranch_scc1 .Lepi0_branch
	s_barrier
.Lepi0_branch:
	s_lshl_b32 s21, s38, 8
	s_ashr_i32 s6, s38, 2
	s_and_b32 s21, s21, 0x300
	s_cmp_lt_u32 s38, 4
	s_cselect_b64 s[62:63], -1, 0
	s_cmp_gt_u32 s38, 3
	s_cselect_b64 s[90:91], -1, 0
	s_lshl_b32 s22, s6, 15
	s_lshl_b32 s2, s2, 8
	s_lshl_b32 s6, s6, 10
	v_or_b32_e32 v132, s21, v200
	s_sub_i32 s2, s2, s22
	s_addk_i32 s6, 0x1a00
	v_add_u32_e32 v0, s6, v132
	v_add_u32_e32 v170, s2, v179
	v_ashrrev_i32_e32 v203, 8, v0
	v_lshrrev_b32_e32 v0, 8, v170
	v_mad_i32_i24 v130, v0, 38, v203
	v_bitop3_b32 v202, s21, v243, v200 bitop3:0xc8
	v_ashrrev_i32_e32 v131, 31, v130
	v_or_b32_e32 v0, v202, v185
	v_lshlrev_b64 v[130:131], 17, v[130:131]
	v_lshl_add_u64 v[130:131], s[40:41], 0, v[130:131]
	v_lshlrev_b32_e32 v0, 1, v0
	v_lshl_add_u64 v[130:131], v[130:131], 0, v[0:1]
	global_load_dwordx4 v[154:157], v[130:131], off
	global_load_dwordx4 v[138:141], v[130:131], off offset:64
	v_lshlrev_b32_e32 v172, 1, v132
	v_mov_b32_e32 v173, v1
	v_lshl_add_u64 v[176:177], s[0:1], 0, v[172:173]
	v_mov_b32_e32 v130, 0
	s_and_b64 vcc, exec, s[62:63]
	v_ashrrev_i32_e32 v171, 31, v170
	v_mov_b32_e32 v146, 0
	v_mov_b32_e32 v147, 0
	v_mov_b32_e32 v148, 0
	v_mov_b32_e32 v149, 0
	v_mov_b32_e32 v158, 0
	v_mov_b32_e32 v159, 0
	v_mov_b32_e32 v160, 0
	v_mov_b32_e32 v161, 0
	s_cbranch_vccnz .LBB0_531
	v_lshlrev_b64 v[132:133], 11, v[170:171]
	v_lshl_add_u64 v[132:133], v[176:177], 0, v[132:133]
	global_load_dwordx4 v[158:161], v[132:133], off
	global_load_dwordx4 v[146:149], v[132:133], off offset:64

.LBB0_609:
	s_add_u32 s24, s16, 0x19c00000
	s_addc_u32 s25, s17, 0
	v_bfe_u32 v16, v8, 4, 2
	s_add_u32 s26, s16, 0x12000000
	v_and_b32_e32 v15, 15, v8
	v_lshlrev_b32_e32 v18, 4, v16
	v_lshlrev_b32_e32 v8, 2, v8
	s_addc_u32 s27, s17, 0
	s_and_b32 s3, s18, 3
	v_lshl_or_b32 v182, s19, 6, v15
	v_lshl_or_b32 v15, v15, 6, v18
	s_lshl_b32 s16, s19, 13
	v_and_b32_e32 v8, 32, v8
	s_mov_b64 s[28:29], 0x80
	v_bitop3_b32 v18, v15, s16, v8 bitop3:0xde
	s_lshl_b32 s16, s3, 12
	s_add_i32 m0, s11, 0x18000
	v_lshl_add_u64 v[6:7], v[6:7], 0, s[28:29]
	v_bitop3_b32 v183, v15, s16, v8 bitop3:0xde
	s_waitcnt vmcnt(4)
	s_barrier
	global_load_lds_dwordx4 v[6:7], off
	v_lshl_add_u64 v[4:5], v[4:5], 0, s[28:29]
	s_add_i32 m0, s11, 0x1a000
	s_add_i32 s16, s11, 0x8000
	s_add_i32 s17, s11, 0xa000
	global_load_lds_dwordx4 v[4:5], off
	v_lshl_add_u64 v[2:3], v[2:3], 0, s[28:29]
	s_mov_b32 m0, s16
	s_add_u32 s18, s52, 0x40080
	global_load_lds_dwordx4 v[2:3], off
	v_lshl_add_u64 v[0:1], v[0:1], 0, s[28:29]
	s_mov_b32 m0, s17
	s_addc_u32 s19, s53, 0
	global_load_lds_dwordx4 v[0:1], off
	s_add_i32 m0, s11, 0x1c000
	v_lshl_add_u64 v[0:1], s[18:19], 0, v[160:161]
	global_load_lds_dwordx4 v[0:1], off
	v_lshl_add_u64 v[0:1], s[18:19], 0, v[162:163]
	s_add_i32 m0, s11, 0x1e000
	v_lshlrev_b32_e32 v17, 3, v16
	global_load_lds_dwordx4 v[0:1], off
	v_lshlrev_b32_e32 v0, 14, v9
	v_and_b32_e32 v0, 0xffff8000, v0
	v_lshl_add_u32 v0, v10, 11, v0
	v_and_b32_e32 v1, 1, v9
	v_lshl_or_b32 v0, v1, 6, v0
	v_lshl_add_u32 v164, v11, 1, v0
	v_lshlrev_b32_e32 v0, 14, v12
	v_and_b32_e32 v0, 0xffff8000, v0
	s_waitcnt vmcnt(6)
	v_lshl_add_u32 v0, v13, 11, v0
	v_and_b32_e32 v1, 1, v12
	v_lshl_or_b32 v0, v1, 6, v0
	s_add_i32 s19, 0, 0x10000
	s_add_i32 s20, 0, 0x14000
	v_lshl_or_b32 v184, s3, 6, v17
	v_cmp_eq_u32_e64 s[36:37], 0, v16
	s_ashr_i32 s18, s4, 31
	v_mov_b32_e32 v165, v161
	v_lshl_add_u32 v166, v14, 1, v0
	v_mov_b32_e32 v167, v161
	v_mov_b64_e32 v[168:169], 0x400
	v_mov_b64_e32 v[170:171], 0x3ff
	v_add_u32_e32 v185, s19, v183
	v_add_u32_e32 v186, 0, v18
	v_add_u32_e32 v187, s20, v183
	s_barrier
	s_branch .LBB0_611
	s_nop 0
	s_nop 0
	s_nop 0
	s_nop 0
	s_nop 0
	s_nop 0
	s_nop 0
	s_nop 0
	s_nop 0
	s_nop 0
.LBB0_610:
	s_or_b64 exec, exec, s[2:3]
	s_and_b64 vcc, exec, s[38:39]
	s_mov_b32 s46, s34
	s_mov_b32 s2, s30
	s_mov_b64 s[52:53], s[42:43]
	s_mov_b64 s[48:49], s[40:41]
	s_cmpk_gt_u32 s5, 0xff
	s_cbranch_scc0 .Lepi1_out
	s_barrier

.LBB0_618:
	ds_read_b128 v[48:51], v185
	ds_read_b128 v[52:55], v185 offset:1024
	ds_read_b128 v[56:59], v185 offset:2048
	ds_read_b128 v[60:63], v185 offset:3072
	s_add_u32 s47, s48, 0xfffc0080
	s_addc_u32 s50, s49, -1
	s_cmp_eq_u32 s35, 12
	s_cselect_b32 s55, s3, s50
	s_cselect_b32 s54, s21, s47
	s_cselect_b32 s53, s22, s33
	s_cselect_b32 s52, s23, s31
	v_lshl_add_u64 v[180:181], s[48:49], 0, v[164:165]
	s_add_i32 m0, s11, 0xc000
	ds_read_b128 v[144:147], v186
	ds_read_b128 v[148:151], v186 offset:1024
	ds_read_b128 v[152:155], v186 offset:2048
	ds_read_b128 v[156:159], v186 offset:3072
	ds_read_b128 v[172:175], v186 offset:4096
	ds_read_b128 v[176:179], v186 offset:5120
	ds_read_b128 v[188:191], v186 offset:6144
	ds_read_b128 v[192:195], v186 offset:7168
	global_load_lds_dwordx4 v[180:181], off
	v_lshl_add_u64 v[180:181], s[48:49], 0, v[166:167]
	s_add_i32 m0, s11, 0xe000
	s_nop 0
	global_load_lds_dwordx4 v[180:181], off
	s_waitcnt lgkmcnt(8)
	s_barrier
	s_waitcnt lgkmcnt(0)
	s_waitcnt lgkmcnt(0)
	v_mfma_f32_16x16x32_bf16 v[140:143], v[48:51], v[144:147], v[140:143]
	v_mfma_f32_16x16x32_bf16 v[136:139], v[56:59], v[144:147], v[136:139]
	v_mfma_f32_16x16x32_bf16 v[124:127], v[48:51], v[152:155], v[124:127]
	v_mfma_f32_16x16x32_bf16 v[120:123], v[56:59], v[152:155], v[120:123]
	v_mfma_f32_16x16x32_bf16 v[108:111], v[48:51], v[172:175], v[108:111]
	v_mfma_f32_16x16x32_bf16 v[104:107], v[56:59], v[172:175], v[104:107]
	v_mfma_f32_16x16x32_bf16 v[92:95], v[48:51], v[188:191], v[92:95]
	v_mfma_f32_16x16x32_bf16 v[88:91], v[56:59], v[188:191], v[88:91]
	v_mfma_f32_16x16x32_bf16 v[140:143], v[52:55], v[148:151], v[140:143]
	v_mfma_f32_16x16x32_bf16 v[136:139], v[60:63], v[148:151], v[136:139]
	v_mfma_f32_16x16x32_bf16 v[124:127], v[52:55], v[156:159], v[124:127]
	v_mfma_f32_16x16x32_bf16 v[120:123], v[60:63], v[156:159], v[120:123]
	v_mfma_f32_16x16x32_bf16 v[108:111], v[52:55], v[176:179], v[108:111]
	v_mfma_f32_16x16x32_bf16 v[104:107], v[60:63], v[176:179], v[104:107]
	v_mfma_f32_16x16x32_bf16 v[92:95], v[52:55], v[192:195], v[92:95]
	v_mfma_f32_16x16x32_bf16 v[88:91], v[60:63], v[192:195], v[88:91]
	s_barrier
	s_add_i32 s47, s19, s10
	v_lshl_add_u64 v[180:181], s[52:53], 0, v[160:161]
	s_mov_b32 m0, s47
	ds_read_b128 v[196:199], v187
	ds_read_b128 v[200:203], v187 offset:1024
	ds_read_b128 v[204:207], v187 offset:2048
	ds_read_b128 v[208:211], v187 offset:3072
	global_load_lds_dwordx4 v[180:181], off
	v_lshl_add_u64 v[212:213], s[52:53], 0, v[162:163]
	s_add_i32 m0, s47, 0x2000
	s_nop 0
	global_load_lds_dwordx4 v[212:213], off
	s_barrier
	s_waitcnt lgkmcnt(0)
	s_waitcnt lgkmcnt(0)
	v_mfma_f32_16x16x32_bf16 v[132:135], v[196:199], v[144:147], v[132:135]
	v_mfma_f32_16x16x32_bf16 v[128:131], v[204:207], v[144:147], v[128:131]
	v_mfma_f32_16x16x32_bf16 v[116:119], v[196:199], v[152:155], v[116:119]
	v_mfma_f32_16x16x32_bf16 v[112:115], v[204:207], v[152:155], v[112:115]
	v_mfma_f32_16x16x32_bf16 v[100:103], v[196:199], v[172:175], v[100:103]
	v_mfma_f32_16x16x32_bf16 v[96:99], v[204:207], v[172:175], v[96:99]
	v_mfma_f32_16x16x32_bf16 v[84:87], v[196:199], v[188:191], v[84:87]
	v_mfma_f32_16x16x32_bf16 v[80:83], v[204:207], v[188:191], v[80:83]
	v_mfma_f32_16x16x32_bf16 v[132:135], v[200:203], v[148:151], v[132:135]
	v_mfma_f32_16x16x32_bf16 v[128:131], v[208:211], v[148:151], v[128:131]
	v_mfma_f32_16x16x32_bf16 v[116:119], v[200:203], v[156:159], v[116:119]
	v_mfma_f32_16x16x32_bf16 v[112:115], v[208:211], v[156:159], v[112:115]
	v_mfma_f32_16x16x32_bf16 v[100:103], v[200:203], v[176:179], v[100:103]
	v_mfma_f32_16x16x32_bf16 v[96:99], v[208:211], v[176:179], v[96:99]
	v_mfma_f32_16x16x32_bf16 v[84:87], v[200:203], v[192:195], v[84:87]
	v_mfma_f32_16x16x32_bf16 v[80:83], v[208:211], v[192:195], v[80:83]
	s_mov_b32 m0, s11
	v_lshl_add_u64 v[214:215], s[54:55], 0, v[160:161]
	s_barrier
	ds_read_b128 v[144:147], v186 offset:16384
	ds_read_b128 v[148:151], v186 offset:17408
	ds_read_b128 v[152:155], v186 offset:18432
	ds_read_b128 v[156:159], v186 offset:19456
	ds_read_b128 v[172:175], v186 offset:20480
	ds_read_b128 v[176:179], v186 offset:21504
	ds_read_b128 v[188:191], v186 offset:22528
	ds_read_b128 v[192:195], v186 offset:23552
	global_load_lds_dwordx4 v[214:215], off
	v_lshl_add_u64 v[216:217], s[54:55], 0, v[162:163]
	s_mov_b32 m0, s12
	s_nop 0
	global_load_lds_dwordx4 v[216:217], off
	s_barrier
	s_waitcnt lgkmcnt(0)
	s_waitcnt lgkmcnt(0)
	v_mfma_f32_16x16x32_bf16 v[76:79], v[48:51], v[144:147], v[76:79]
	v_mfma_f32_16x16x32_bf16 v[72:75], v[56:59], v[144:147], v[72:75]
	v_mfma_f32_16x16x32_bf16 v[44:47], v[48:51], v[152:155], v[44:47]
	v_mfma_f32_16x16x32_bf16 v[40:43], v[56:59], v[152:155], v[40:43]
	v_mfma_f32_16x16x32_bf16 v[28:31], v[48:51], v[172:175], v[28:31]
	v_mfma_f32_16x16x32_bf16 v[24:27], v[56:59], v[172:175], v[24:27]
	v_mfma_f32_16x16x32_bf16 v[12:15], v[48:51], v[188:191], v[12:15]
	v_mfma_f32_16x16x32_bf16 v[8:11], v[56:59], v[188:191], v[8:11]
	v_mfma_f32_16x16x32_bf16 v[76:79], v[52:55], v[148:151], v[76:79]
	v_mfma_f32_16x16x32_bf16 v[72:75], v[60:63], v[148:151], v[72:75]
	v_mfma_f32_16x16x32_bf16 v[44:47], v[52:55], v[156:159], v[44:47]
	v_mfma_f32_16x16x32_bf16 v[40:43], v[60:63], v[156:159], v[40:43]
	v_mfma_f32_16x16x32_bf16 v[28:31], v[52:55], v[176:179], v[28:31]
	v_mfma_f32_16x16x32_bf16 v[24:27], v[60:63], v[176:179], v[24:27]
	v_mfma_f32_16x16x32_bf16 v[12:15], v[52:55], v[192:195], v[12:15]
	v_mfma_f32_16x16x32_bf16 v[8:11], v[60:63], v[192:195], v[8:11]
	s_barrier
	s_add_u32 s50, s52, 0x40000
	s_addc_u32 s51, s53, 0
	s_add_i32 s47, s20, s10
	v_lshl_add_u64 v[48:49], s[50:51], 0, v[160:161]
	s_mov_b32 m0, s47
	s_nop 0
	global_load_lds_dwordx4 v[48:49], off
	v_lshl_add_u64 v[48:49], s[50:51], 0, v[162:163]
	s_add_i32 m0, s47, 0x2000
	s_nop 0
	global_load_lds_dwordx4 v[48:49], off
	s_waitcnt vmcnt(6)
	s_barrier
	v_mfma_f32_16x16x32_bf16 v[36:39], v[196:199], v[152:155], v[36:39]
	v_mfma_f32_16x16x32_bf16 v[32:35], v[204:207], v[152:155], v[32:35]
	v_mfma_f32_16x16x32_bf16 v[20:23], v[196:199], v[172:175], v[20:23]
	v_mfma_f32_16x16x32_bf16 v[16:19], v[204:207], v[172:175], v[16:19]
	v_mfma_f32_16x16x32_bf16 v[4:7], v[196:199], v[188:191], v[4:7]
	v_mfma_f32_16x16x32_bf16 v[0:3], v[204:207], v[188:191], v[0:3]
	v_mfma_f32_16x16x32_bf16 v[48:51], v[196:199], v[144:147], v[68:71]
	v_mfma_f32_16x16x32_bf16 v[52:55], v[204:207], v[144:147], v[64:67]
	v_mfma_f32_16x16x32_bf16 v[36:39], v[200:203], v[156:159], v[36:39]
	v_mfma_f32_16x16x32_bf16 v[32:35], v[208:211], v[156:159], v[32:35]
	v_mfma_f32_16x16x32_bf16 v[20:23], v[200:203], v[176:179], v[20:23]
	v_mfma_f32_16x16x32_bf16 v[16:19], v[208:211], v[176:179], v[16:19]
	v_mfma_f32_16x16x32_bf16 v[4:7], v[200:203], v[192:195], v[4:7]
	v_mfma_f32_16x16x32_bf16 v[0:3], v[208:211], v[192:195], v[0:3]
	v_mfma_f32_16x16x32_bf16 v[48:51], v[200:203], v[148:151], v[48:51]
	v_mfma_f32_16x16x32_bf16 v[52:55], v[208:211], v[148:151], v[52:55]
	s_add_i32 s47, 0, 0x18000
	v_add_u32_e32 v68, s47, v183
	s_barrier
	ds_read_b128 v[56:59], v68
	ds_read_b128 v[60:63], v68 offset:1024
	ds_read_b128 v[64:67], v68 offset:2048
	ds_read_b128 v[68:71], v68 offset:3072
	s_add_u32 s50, s54, 0x40000
	s_addc_u32 s51, s55, 0
	s_mov_b32 m0, s13
	v_lshl_add_u64 v[196:197], s[50:51], 0, v[160:161]
	ds_read_b128 v[144:147], v186 offset:32768
	ds_read_b128 v[148:151], v186 offset:33792
	ds_read_b128 v[152:155], v186 offset:34816
	ds_read_b128 v[156:159], v186 offset:35840
	ds_read_b128 v[172:175], v186 offset:36864
	ds_read_b128 v[176:179], v186 offset:37888
	ds_read_b128 v[188:191], v186 offset:38912
	ds_read_b128 v[192:195], v186 offset:39936
	global_load_lds_dwordx4 v[196:197], off
	v_lshl_add_u64 v[196:197], s[50:51], 0, v[162:163]
	s_mov_b32 m0, s14
	s_nop 0
	global_load_lds_dwordx4 v[196:197], off
	s_waitcnt lgkmcnt(8)
	s_barrier
	s_waitcnt lgkmcnt(0)
	s_waitcnt lgkmcnt(0)
	v_mfma_f32_16x16x32_bf16 v[140:143], v[56:59], v[144:147], v[140:143]
	v_mfma_f32_16x16x32_bf16 v[136:139], v[64:67], v[144:147], v[136:139]
	v_mfma_f32_16x16x32_bf16 v[124:127], v[56:59], v[152:155], v[124:127]
	v_mfma_f32_16x16x32_bf16 v[120:123], v[64:67], v[152:155], v[120:123]
	v_mfma_f32_16x16x32_bf16 v[108:111], v[56:59], v[172:175], v[108:111]
	v_mfma_f32_16x16x32_bf16 v[104:107], v[64:67], v[172:175], v[104:107]
	v_mfma_f32_16x16x32_bf16 v[92:95], v[56:59], v[188:191], v[92:95]
	v_mfma_f32_16x16x32_bf16 v[88:91], v[64:67], v[188:191], v[88:91]
	v_mfma_f32_16x16x32_bf16 v[140:143], v[60:63], v[148:151], v[140:143]
	v_mfma_f32_16x16x32_bf16 v[136:139], v[68:71], v[148:151], v[136:139]
	v_mfma_f32_16x16x32_bf16 v[124:127], v[60:63], v[156:159], v[124:127]
	v_mfma_f32_16x16x32_bf16 v[120:123], v[68:71], v[156:159], v[120:123]
	v_mfma_f32_16x16x32_bf16 v[108:111], v[60:63], v[176:179], v[108:111]
	v_mfma_f32_16x16x32_bf16 v[104:107], v[68:71], v[176:179], v[104:107]
	v_mfma_f32_16x16x32_bf16 v[92:95], v[60:63], v[192:195], v[92:95]
	v_mfma_f32_16x16x32_bf16 v[88:91], v[68:71], v[192:195], v[88:91]
	s_barrier
	s_add_i32 s54, 0, 0x1c000
	s_add_i32 s47, s47, s10
	v_add_u32_e32 v208, s54, v183
	v_lshl_add_u64 v[180:181], v[180:181], 0, s[28:29]
	s_mov_b32 m0, s47
	ds_read_b128 v[196:199], v208
	ds_read_b128 v[200:203], v208 offset:1024
	ds_read_b128 v[204:207], v208 offset:2048
	ds_read_b128 v[208:211], v208 offset:3072
	global_load_lds_dwordx4 v[180:181], off
	v_lshl_add_u64 v[180:181], v[212:213], 0, s[28:29]
	s_add_i32 m0, s47, 0x2000
	s_nop 0
	global_load_lds_dwordx4 v[180:181], off
	s_barrier
	s_waitcnt lgkmcnt(0)
	s_waitcnt lgkmcnt(0)
	v_mfma_f32_16x16x32_bf16 v[132:135], v[196:199], v[144:147], v[132:135]
	v_mfma_f32_16x16x32_bf16 v[128:131], v[204:207], v[144:147], v[128:131]
	v_mfma_f32_16x16x32_bf16 v[116:119], v[196:199], v[152:155], v[116:119]
	v_mfma_f32_16x16x32_bf16 v[112:115], v[204:207], v[152:155], v[112:115]
	v_mfma_f32_16x16x32_bf16 v[100:103], v[196:199], v[172:175], v[100:103]
	v_mfma_f32_16x16x32_bf16 v[96:99], v[204:207], v[172:175], v[96:99]
	v_mfma_f32_16x16x32_bf16 v[84:87], v[196:199], v[188:191], v[84:87]
	v_mfma_f32_16x16x32_bf16 v[80:83], v[204:207], v[188:191], v[80:83]
	v_mfma_f32_16x16x32_bf16 v[132:135], v[200:203], v[148:151], v[132:135]
	v_mfma_f32_16x16x32_bf16 v[128:131], v[208:211], v[148:151], v[128:131]
	v_mfma_f32_16x16x32_bf16 v[116:119], v[200:203], v[156:159], v[116:119]
	v_mfma_f32_16x16x32_bf16 v[112:115], v[208:211], v[156:159], v[112:115]
	v_mfma_f32_16x16x32_bf16 v[100:103], v[200:203], v[176:179], v[100:103]
	v_mfma_f32_16x16x32_bf16 v[96:99], v[208:211], v[176:179], v[96:99]
	v_mfma_f32_16x16x32_bf16 v[84:87], v[200:203], v[192:195], v[84:87]
	v_mfma_f32_16x16x32_bf16 v[80:83], v[208:211], v[192:195], v[80:83]
	s_mov_b32 m0, s16
	v_lshl_add_u64 v[180:181], v[214:215], 0, s[28:29]
	s_barrier
	ds_read_b128 v[144:147], v186 offset:49152
	ds_read_b128 v[148:151], v186 offset:50176
	ds_read_b128 v[152:155], v186 offset:51200
	ds_read_b128 v[156:159], v186 offset:52224
	ds_read_b128 v[172:175], v186 offset:53248
	ds_read_b128 v[176:179], v186 offset:54272
	ds_read_b128 v[188:191], v186 offset:55296
	ds_read_b128 v[192:195], v186 offset:56320
	global_load_lds_dwordx4 v[180:181], off
	v_lshl_add_u64 v[180:181], v[216:217], 0, s[28:29]
	s_mov_b32 m0, s17
	s_nop 0
	global_load_lds_dwordx4 v[180:181], off
	s_barrier
	s_waitcnt lgkmcnt(0)
	s_waitcnt lgkmcnt(0)
	v_mfma_f32_16x16x32_bf16 v[76:79], v[56:59], v[144:147], v[76:79]
	v_mfma_f32_16x16x32_bf16 v[72:75], v[64:67], v[144:147], v[72:75]
	v_mfma_f32_16x16x32_bf16 v[44:47], v[56:59], v[152:155], v[44:47]
	v_mfma_f32_16x16x32_bf16 v[40:43], v[64:67], v[152:155], v[40:43]
	v_mfma_f32_16x16x32_bf16 v[28:31], v[56:59], v[172:175], v[28:31]
	v_mfma_f32_16x16x32_bf16 v[24:27], v[64:67], v[172:175], v[24:27]
	v_mfma_f32_16x16x32_bf16 v[12:15], v[56:59], v[188:191], v[12:15]
	v_mfma_f32_16x16x32_bf16 v[8:11], v[64:67], v[188:191], v[8:11]
	v_mfma_f32_16x16x32_bf16 v[76:79], v[60:63], v[148:151], v[76:79]
	v_mfma_f32_16x16x32_bf16 v[72:75], v[68:71], v[148:151], v[72:75]
	v_mfma_f32_16x16x32_bf16 v[44:47], v[60:63], v[156:159], v[44:47]
	v_mfma_f32_16x16x32_bf16 v[40:43], v[68:71], v[156:159], v[40:43]
	v_mfma_f32_16x16x32_bf16 v[28:31], v[60:63], v[176:179], v[28:31]
	v_mfma_f32_16x16x32_bf16 v[24:27], v[68:71], v[176:179], v[24:27]
	v_mfma_f32_16x16x32_bf16 v[12:15], v[60:63], v[192:195], v[12:15]
	v_mfma_f32_16x16x32_bf16 v[8:11], v[68:71], v[192:195], v[8:11]
	s_barrier
	s_add_u32 s50, s52, 0x40080
	s_addc_u32 s51, s53, 0
	s_add_i32 s47, s54, s10
	v_lshl_add_u64 v[56:57], s[50:51], 0, v[160:161]
	s_mov_b32 m0, s47
	s_nop 0
	global_load_lds_dwordx4 v[56:57], off
	v_lshl_add_u64 v[56:57], s[50:51], 0, v[162:163]
	s_add_i32 m0, s47, 0x2000
	s_nop 0
	global_load_lds_dwordx4 v[56:57], off
	s_waitcnt vmcnt(6)
	s_barrier
	v_mfma_f32_16x16x32_bf16 v[48:51], v[196:199], v[144:147], v[48:51]
	v_mfma_f32_16x16x32_bf16 v[68:71], v[200:203], v[148:151], v[48:51]
	v_mfma_f32_16x16x32_bf16 v[48:51], v[204:207], v[144:147], v[52:55]
	v_mfma_f32_16x16x32_bf16 v[36:39], v[196:199], v[152:155], v[36:39]
	v_mfma_f32_16x16x32_bf16 v[32:35], v[204:207], v[152:155], v[32:35]
	v_mfma_f32_16x16x32_bf16 v[20:23], v[196:199], v[172:175], v[20:23]
	v_mfma_f32_16x16x32_bf16 v[16:19], v[204:207], v[172:175], v[16:19]
	v_mfma_f32_16x16x32_bf16 v[4:7], v[196:199], v[188:191], v[4:7]
	v_mfma_f32_16x16x32_bf16 v[0:3], v[204:207], v[188:191], v[0:3]
	v_mfma_f32_16x16x32_bf16 v[64:67], v[208:211], v[148:151], v[48:51]
	v_mfma_f32_16x16x32_bf16 v[36:39], v[200:203], v[156:159], v[36:39]
	v_mfma_f32_16x16x32_bf16 v[32:35], v[208:211], v[156:159], v[32:35]
	v_mfma_f32_16x16x32_bf16 v[20:23], v[200:203], v[176:179], v[20:23]
	v_mfma_f32_16x16x32_bf16 v[16:19], v[208:211], v[176:179], v[16:19]
	v_mfma_f32_16x16x32_bf16 v[4:7], v[200:203], v[192:195], v[4:7]
	v_mfma_f32_16x16x32_bf16 v[0:3], v[208:211], v[192:195], v[0:3]
	s_add_i32 s35, s35, 2
	s_add_u32 s48, s48, 0x100
	s_addc_u32 s49, s49, 0
	s_add_u32 s31, s31, 0x100
	s_addc_u32 s33, s33, 0
	s_cmp_gt_u32 s35, 13
	s_barrier
	s_cbranch_scc0 .LBB0_618
	s_cmpk_gt_u32 s5, 0xff
	s_cbranch_scc1 .Lepi0_out
	s_barrier
.Lepi0_out:
	v_and_b32_e32 v145, 64, v229
	v_xor_b32_e32 v144, 16, v229
	v_add_u32_e32 v145, 64, v145
	v_cmp_lt_i32_e32 vcc, v144, v145
	v_lshl_or_b32 v172, s46, 8, v184
	v_ashrrev_i32_e32 v173, 31, v172
	v_cndmask_b32_e32 v144, v229, v144, vcc
	v_lshl_add_u32 v174, s2, 8, v182
	v_lshlrev_b32_e32 v189, 2, v144
	v_xor_b32_e32 v144, 32, v229
	v_lshlrev_b64 v[206:207], 2, v[172:173]
	v_cmp_lt_i32_e32 vcc, v144, v145
	v_ashrrev_i32_e32 v175, 31, v174
	v_lshl_add_u64 v[176:177], s[44:45], 0, v[206:207]
	v_cndmask_b32_e32 v144, v229, v144, vcc
	v_lshlrev_b64 v[208:209], 12, v[174:175]
	v_lshl_add_u64 v[56:57], s[56:57], 0, v[206:207]
	v_lshlrev_b32_e32 v188, 2, v144
	v_lshl_add_u64 v[144:145], v[176:177], 0, v[208:209]
	global_load_dwordx4 v[52:55], v[56:57], off offset:16
	global_load_dwordx4 v[60:63], v[56:57], off
	global_load_dwordx4 v[48:51], v[56:57], off offset:144
	s_nop 0
	global_load_dwordx4 v[56:59], v[56:57], off offset:128
	s_nop 0
	global_load_dwordx4 v[190:193], v[144:145], off offset:16
	global_load_dwordx4 v[194:197], v[144:145], off
	global_load_dwordx4 v[198:201], v[144:145], off offset:144
	global_load_dwordx4 v[202:205], v[144:145], off offset:128
	v_or_b32_e32 v178, 16, v174
	v_ashrrev_i32_e32 v179, 31, v178
	v_lshlrev_b64 v[180:181], 12, v[178:179]
	v_lshl_add_u64 v[148:149], v[176:177], 0, v[180:181]
	global_load_dwordx4 v[152:155], v[148:149], off offset:16
	global_load_dwordx4 v[156:159], v[148:149], off
	global_load_dwordx4 v[144:147], v[148:149], off offset:144
	s_nop 0
	global_load_dwordx4 v[148:151], v[148:149], off offset:128
	s_waitcnt vmcnt(0)
	v_pk_add_f32 v[136:137], v[136:137], v[190:191]
	v_pk_add_f32 v[194:195], v[140:141], v[194:195]
	v_pk_add_f32 v[198:199], v[128:129], v[198:199]
	v_lshl_add_u64 v[128:129], s[78:79], 0, v[208:209]
	v_pk_add_f32 v[196:197], v[142:143], v[196:197]
	v_pk_mul_f32 v[212:213], v[194:195], v[194:195]
	v_pk_add_f32 v[190:191], v[132:133], v[202:203]
	v_lshl_add_u64 v[128:129], v[128:129], 0, v[206:207]
	v_pk_mul_f32 v[210:211], v[196:197], v[196:197]
	v_pk_add_f32 v[138:139], v[138:139], v[192:193]
	v_pk_add_f32 v[192:193], v[134:135], v[204:205]
	v_pk_mul_f32 v[204:205], v[190:191], v[190:191]
	v_pk_add_f32 v[200:201], v[130:131], v[200:201]
	global_store_dwordx4 v[128:129], v[194:197], off nt
	global_store_dwordx4 v[128:129], v[136:139], off offset:16 nt
	global_store_dwordx4 v[128:129], v[190:193], off offset:128 nt
	global_store_dwordx4 v[128:129], v[198:201], off offset:144 nt
	v_pk_mul_f32 v[134:135], v[56:57], v[190:191]
	v_add_f32_e32 v190, v212, v213
	v_add_f32_e32 v190, v210, v190
	v_pk_mul_f32 v[216:217], v[136:137], v[136:137]
	v_add_f32_e32 v190, v211, v190
	v_add_f32_e32 v190, v216, v190
	v_pk_mul_f32 v[214:215], v[138:139], v[138:139]
	v_add_f32_e32 v190, v217, v190
	v_add_f32_e32 v190, v214, v190
	v_add_f32_e32 v190, v215, v190
	v_add_f32_e32 v190, v204, v190
	v_pk_mul_f32 v[202:203], v[192:193], v[192:193]
	v_add_f32_e32 v190, v205, v190
	v_add_f32_e32 v190, v202, v190
	v_pk_mul_f32 v[220:221], v[198:199], v[198:199]
	v_add_f32_e32 v190, v203, v190
	v_add_f32_e32 v190, v220, v190
	v_pk_mul_f32 v[218:219], v[200:201], v[200:201]
	v_add_f32_e32 v190, v221, v190
	v_add_f32_e32 v190, v218, v190
	v_pk_mul_f32 v[128:129], v[62:63], v[196:197]
	v_add_f32_e32 v196, v219, v190
	v_lshlrev_b64 v[190:191], 11, v[174:175]
	v_pk_mul_f32 v[142:143], v[60:61], v[194:195]
	v_pk_mul_f32 v[130:131], v[52:53], v[136:137]
	v_pk_mul_f32 v[132:133], v[54:55], v[138:139]
	v_lshl_add_u64 v[190:191], s[24:25], 0, v[190:191]
	v_pk_mul_f32 v[136:137], v[58:59], v[192:193]
	v_pk_mul_f32 v[138:139], v[48:49], v[198:199]
	v_pk_mul_f32 v[140:141], v[50:51], v[200:201]
	v_lshl_add_u64 v[194:195], v[172:173], 1, v[190:191]
	v_cvt_pk_bf16_f32 v190, v142, v143
	v_cvt_pk_bf16_f32 v191, v128, v129
	v_cvt_pk_bf16_f32 v192, v130, v131
	v_cvt_pk_bf16_f32 v193, v132, v133
	v_cvt_pk_bf16_f32 v128, v134, v135
	v_cvt_pk_bf16_f32 v129, v136, v137
	v_cvt_pk_bf16_f32 v130, v138, v139
	v_cvt_pk_bf16_f32 v131, v140, v141
	global_store_dwordx4 v[194:195], v[190:193], off nt
	global_store_dwordx4 v[194:195], v[128:131], off offset:64 nt
	ds_bpermute_b32 v128, v189, v196
	s_waitcnt lgkmcnt(0)
	v_add_f32_e32 v128, v196, v128
	ds_bpermute_b32 v129, v188, v128
	s_and_saveexec_b64 s[2:3], s[36:37]
	s_cbranch_execz .LBB0_621
	v_lshl_add_u64 v[130:131], v[174:175], 2, s[26:27]
	s_waitcnt lgkmcnt(0)
	v_add_f32_e32 v128, v128, v129
	global_atomic_add_f32 v[130:131], v128, off

.LBB0_698:
	v_readlane_b32 s20, v254, 1
	v_readlane_b32 s21, v254, 2
	v_readlane_b32 s22, v254, 3
	v_readlane_b32 s23, v254, 4
	v_readlane_b32 s24, v254, 5
	v_readlane_b32 s25, v254, 6
	v_readlane_b32 s26, v254, 7
	v_readlane_b32 s27, v254, 8
	s_mov_b64 s[20:21], s[24:25]
	s_add_u32 s96, s20, 0x2c00
	s_addc_u32 s97, s21, 0
	s_add_u32 s86, s20, 0x5800
	s_addc_u32 s87, s21, 0
	s_add_u32 s28, s2, 0x21c00000
	s_addc_u32 s29, s3, 0
	s_add_u32 s30, s2, 0x14000000
	v_lshrrev_b32_e32 v16, 1, v8
	s_addc_u32 s31, s3, 0
	v_and_b32_e32 v16, 24, v16
	s_add_u32 s34, s2, 0x12000000
	v_and_b32_e32 v15, 15, v8
	v_lshlrev_b32_e32 v17, 1, v16
	v_lshlrev_b32_e32 v18, 2, v8
	s_addc_u32 s35, s3, 0
	v_lshl_or_b32 v17, v15, 6, v17
	s_lshl_b32 s2, s10, 13
	v_and_b32_e32 v18, 32, v18
	v_bitop3_b32 v19, v17, s2, v18 bitop3:0xde
	s_lshl_b32 s2, s17, 5
	s_mov_b64 s[52:53], 0x80
	s_and_b32 s20, s2, 0x60
	s_add_i32 m0, s12, 0x18000
	v_lshl_add_u64 v[6:7], v[6:7], 0, s[52:53]
	s_lshl_b32 s2, s20, 7
	s_waitcnt vmcnt(4)
	s_barrier
	global_load_lds_dwordx4 v[6:7], off
	v_lshl_add_u64 v[4:5], v[4:5], 0, s[52:53]
	s_add_i32 m0, s12, 0x1a000
	s_add_i32 s17, s12, 0x8000
	s_add_i32 s18, s12, 0xa000
	v_bitop3_b32 v232, v17, s2, v18 bitop3:0xde
	global_load_lds_dwordx4 v[4:5], off
	v_lshl_add_u64 v[2:3], v[2:3], 0, s[52:53]
	s_mov_b32 m0, s17
	s_add_u32 s2, s0, 0x40080
	global_load_lds_dwordx4 v[2:3], off
	v_lshl_add_u64 v[0:1], v[0:1], 0, s[52:53]
	s_mov_b32 m0, s18
	s_addc_u32 s3, s1, 0
	global_load_lds_dwordx4 v[0:1], off
	s_add_i32 m0, s12, 0x1c000
	v_lshl_add_u64 v[0:1], s[2:3], 0, v[160:161]
	global_load_lds_dwordx4 v[0:1], off
	v_lshl_add_u64 v[0:1], s[2:3], 0, v[162:163]
	s_add_i32 m0, s12, 0x1e000
	v_cmp_eq_u32_e64 s[38:39], 15, v15
	global_load_lds_dwordx4 v[0:1], off
	s_nop 0
	v_cndmask_b32_e64 v0, -1, 3, s[38:39]
	v_cmp_ne_u32_e32 vcc, 14, v15
	v_cmp_eq_u32_e64 s[42:43], 0, v15
	v_and_b32_e32 v1, 1, v9
	v_cndmask_b32_e32 v233, 2, v0, vcc
	v_cmp_eq_u32_e32 vcc, 1, v15
	s_waitcnt vmcnt(6)
	v_or_b32_e32 v235, s20, v16
	s_add_i32 s20, 0, 0x10000
	v_cndmask_b32_e64 v0, -1, 1, vcc
	v_cndmask_b32_e64 v234, v0, 0, s[42:43]
	v_and_b32_e32 v0, 14, v8
	v_cmp_eq_u32_e64 s[74:75], 14, v0
	v_lshlrev_b32_e32 v0, 14, v9
	v_and_b32_e32 v0, 0xffff8000, v0
	v_lshl_add_u32 v0, v10, 11, v0
	v_lshl_or_b32 v0, v1, 6, v0
	v_lshl_add_u32 v166, v11, 1, v0
	v_lshlrev_b32_e32 v0, 14, v12
	v_and_b32_e32 v0, 0xffff8000, v0
	v_lshl_add_u32 v0, v13, 11, v0
	v_and_b32_e32 v1, 1, v12
	v_lshl_or_b32 v0, v1, 6, v0
	s_add_i32 s21, 0, 0x14000
	v_lshl_or_b32 v231, s10, 6, v15
	v_cmp_ne_u32_e64 s[36:37], 15, v15
	v_cmp_ne_u32_e64 s[40:41], 0, v15
	v_cmp_gt_u32_e64 s[70:71], 2, v15
	s_ashr_i32 s19, s4, 31
	v_mov_b32_e32 v167, v165
	v_lshl_add_u32 v168, v14, 1, v0
	v_mov_b32_e32 v169, v165
	v_mov_b64_e32 v[170:171], 0x1600
	v_mov_b64_e32 v[172:173], 0x15ff
	v_add_u32_e32 v236, s20, v232
	v_add_u32_e32 v237, 0, v19
	v_add_u32_e32 v238, s21, v232
	v_mov_b32_e32 v239, 0x358637bd
	s_mov_b32 s33, 0x800000
	s_movk_i32 s65, 0xb00
	s_mov_b32 s54, 0xbf38aa3b
	s_mov_b32 s56, 0x3e6d3388
	s_mov_b32 s58, 0x3f07dc22
	s_mov_b32 s64, 0xbf3a00e3
	s_mov_b32 s66, 0x3f35f0e3
	s_mov_b32 s68, 0xbe11a98e
	s_mov_b32 s72, 0x3e027906
	s_mov_b64 s[22:23], s[26:27]
	s_barrier
	s_branch .LBB0_700
	s_nop 0
	s_nop 0
	s_nop 0
	s_nop 0
	s_nop 0
	s_nop 0
	s_nop 0
	s_nop 0
	s_nop 0
	s_nop 0
.LBB0_699:
	s_or_b64 exec, exec, s[0:1]
	s_and_b64 vcc, exec, s[76:77]
	s_mov_b32 s88, s2
	s_mov_b32 s84, s62
	s_mov_b64 s[0:1], s[24:25]
	s_mov_b64 s[90:91], s[26:27]
	s_cmpk_gt_u32 s5, 0xff
	s_cbranch_scc0 .Lepi1_ffnin
	s_barrier

.LBB0_703:
	ds_read_b128 v[44:47], v236
	ds_read_b128 v[48:51], v236 offset:1024
	ds_read_b128 v[52:55], v236 offset:2048
	ds_read_b128 v[56:59], v236 offset:3072
	s_add_u32 s0, vcc_lo, 0xfffc0080
	s_addc_u32 s1, vcc_hi, -1
	s_cmp_eq_u32 s59, 12
	s_cselect_b32 s91, s22, s1
	s_cselect_b32 s90, s23, s0
	s_cselect_b32 s1, s3, s57
	s_cselect_b32 s0, s51, s55
	v_lshl_add_u64 v[190:191], vcc, 0, v[166:167]
	s_add_i32 m0, s12, 0xc000
	ds_read_b128 v[68:71], v237
	ds_read_b128 v[72:75], v237 offset:1024
	ds_read_b128 v[76:79], v237 offset:2048
	ds_read_b128 v[80:83], v237 offset:3072
	ds_read_b128 v[174:177], v237 offset:4096
	ds_read_b128 v[178:181], v237 offset:5120
	ds_read_b128 v[182:185], v237 offset:6144
	ds_read_b128 v[186:189], v237 offset:7168
	global_load_lds_dwordx4 v[190:191], off
	v_lshl_add_u64 v[190:191], vcc, 0, v[168:169]
	s_add_i32 m0, s12, 0xe000
	s_nop 0
	global_load_lds_dwordx4 v[190:191], off
	s_waitcnt lgkmcnt(8)
	s_barrier
	s_waitcnt lgkmcnt(0)
	s_waitcnt lgkmcnt(0)
	v_mfma_f32_16x16x32_bf16 v[156:159], v[44:47], v[68:71], v[156:159]
	v_mfma_f32_16x16x32_bf16 v[132:135], v[52:55], v[68:71], v[132:135]
	v_mfma_f32_16x16x32_bf16 v[152:155], v[44:47], v[76:79], v[152:155]
	v_mfma_f32_16x16x32_bf16 v[128:131], v[52:55], v[76:79], v[128:131]
	v_mfma_f32_16x16x32_bf16 v[140:143], v[44:47], v[174:177], v[140:143]
	v_mfma_f32_16x16x32_bf16 v[104:107], v[52:55], v[174:177], v[104:107]
	v_mfma_f32_16x16x32_bf16 v[144:147], v[44:47], v[182:185], v[144:147]
	v_mfma_f32_16x16x32_bf16 v[108:111], v[52:55], v[182:185], v[108:111]
	v_mfma_f32_16x16x32_bf16 v[156:159], v[48:51], v[72:75], v[156:159]
	v_mfma_f32_16x16x32_bf16 v[132:135], v[56:59], v[72:75], v[132:135]
	v_mfma_f32_16x16x32_bf16 v[152:155], v[48:51], v[80:83], v[152:155]
	v_mfma_f32_16x16x32_bf16 v[128:131], v[56:59], v[80:83], v[128:131]
	v_mfma_f32_16x16x32_bf16 v[140:143], v[48:51], v[178:181], v[140:143]
	v_mfma_f32_16x16x32_bf16 v[104:107], v[56:59], v[178:181], v[104:107]
	v_mfma_f32_16x16x32_bf16 v[144:147], v[48:51], v[186:189], v[144:147]
	v_mfma_f32_16x16x32_bf16 v[108:111], v[56:59], v[186:189], v[108:111]
	s_barrier
	s_add_i32 s60, s20, s11
	v_lshl_add_u64 v[214:215], s[0:1], 0, v[160:161]
	s_mov_b32 m0, s60
	ds_read_b128 v[190:193], v238
	ds_read_b128 v[194:197], v238 offset:1024
	ds_read_b128 v[198:201], v238 offset:2048
	ds_read_b128 v[202:205], v238 offset:3072
	global_load_lds_dwordx4 v[214:215], off
	v_lshl_add_u64 v[216:217], s[0:1], 0, v[162:163]
	s_add_i32 m0, s60, 0x2000
	s_nop 0
	global_load_lds_dwordx4 v[216:217], off
	s_barrier
	s_waitcnt lgkmcnt(0)
	s_waitcnt lgkmcnt(0)
	v_mfma_f32_16x16x32_bf16 v[148:151], v[190:193], v[68:71], v[148:151]
	v_mfma_f32_16x16x32_bf16 v[68:71], v[198:201], v[68:71], v[124:127]
	v_mfma_f32_16x16x32_bf16 v[148:151], v[194:197], v[72:75], v[148:151]
	v_mfma_f32_16x16x32_bf16 v[68:71], v[202:205], v[72:75], v[68:71]
	v_mfma_f32_16x16x32_bf16 v[72:75], v[190:193], v[76:79], v[120:123]
	v_mfma_f32_16x16x32_bf16 v[76:79], v[198:201], v[76:79], v[112:115]
	v_mfma_f32_16x16x32_bf16 v[100:103], v[198:201], v[174:177], v[100:103]
	v_mfma_f32_16x16x32_bf16 v[112:115], v[190:193], v[182:185], v[136:139]
	v_mfma_f32_16x16x32_bf16 v[96:99], v[198:201], v[182:185], v[96:99]
	v_mfma_f32_16x16x32_bf16 v[72:75], v[194:197], v[80:83], v[72:75]
	v_mfma_f32_16x16x32_bf16 v[76:79], v[202:205], v[80:83], v[76:79]
	v_mfma_f32_16x16x32_bf16 v[80:83], v[190:193], v[174:177], v[116:119]
	v_mfma_f32_16x16x32_bf16 v[100:103], v[202:205], v[178:181], v[100:103]
	v_mfma_f32_16x16x32_bf16 v[136:139], v[194:197], v[186:189], v[112:115]
	v_mfma_f32_16x16x32_bf16 v[96:99], v[202:205], v[186:189], v[96:99]
	v_mfma_f32_16x16x32_bf16 v[80:83], v[194:197], v[178:181], v[80:83]
	s_mov_b32 m0, s12
	v_lshl_add_u64 v[218:219], s[90:91], 0, v[160:161]
	s_barrier
	ds_read_b128 v[112:115], v237 offset:16384
	ds_read_b128 v[116:119], v237 offset:17408
	ds_read_b128 v[120:123], v237 offset:18432
	ds_read_b128 v[124:127], v237 offset:19456
	ds_read_b128 v[174:177], v237 offset:20480
	ds_read_b128 v[178:181], v237 offset:21504
	ds_read_b128 v[182:185], v237 offset:22528
	ds_read_b128 v[186:189], v237 offset:23552
	global_load_lds_dwordx4 v[218:219], off
	v_lshl_add_u64 v[220:221], s[90:91], 0, v[162:163]
	s_mov_b32 m0, s13
	s_nop 0
	global_load_lds_dwordx4 v[220:221], off
	s_barrier
	s_waitcnt lgkmcnt(0)
	s_waitcnt lgkmcnt(0)
	v_mfma_f32_16x16x32_bf16 v[92:95], v[44:47], v[112:115], v[92:95]
	v_mfma_f32_16x16x32_bf16 v[40:43], v[52:55], v[112:115], v[40:43]
	v_mfma_f32_16x16x32_bf16 v[88:91], v[44:47], v[120:123], v[88:91]
	v_mfma_f32_16x16x32_bf16 v[36:39], v[52:55], v[120:123], v[36:39]
	v_mfma_f32_16x16x32_bf16 v[60:63], v[44:47], v[174:177], v[60:63]
	v_mfma_f32_16x16x32_bf16 v[8:11], v[52:55], v[174:177], v[8:11]
	v_mfma_f32_16x16x32_bf16 v[16:19], v[52:55], v[182:185], v[16:19]
	v_mfma_f32_16x16x32_bf16 v[92:95], v[48:51], v[116:119], v[92:95]
	v_mfma_f32_16x16x32_bf16 v[40:43], v[56:59], v[116:119], v[40:43]
	v_mfma_f32_16x16x32_bf16 v[88:91], v[48:51], v[124:127], v[88:91]
	v_mfma_f32_16x16x32_bf16 v[36:39], v[56:59], v[124:127], v[36:39]
	v_mfma_f32_16x16x32_bf16 v[60:63], v[48:51], v[178:181], v[60:63]
	v_mfma_f32_16x16x32_bf16 v[8:11], v[56:59], v[178:181], v[8:11]
	v_mfma_f32_16x16x32_bf16 v[44:47], v[44:47], v[182:185], v[64:67]
	v_mfma_f32_16x16x32_bf16 v[16:19], v[56:59], v[186:189], v[16:19]
	v_mfma_f32_16x16x32_bf16 v[44:47], v[48:51], v[186:189], v[44:47]
	s_barrier
	s_add_u32 s60, s0, 0x40000
	s_addc_u32 s61, s1, 0
	s_add_i32 s63, s21, s11
	v_lshl_add_u64 v[48:49], s[60:61], 0, v[160:161]
	s_mov_b32 m0, s63
	s_nop 0
	global_load_lds_dwordx4 v[48:49], off
	v_lshl_add_u64 v[48:49], s[60:61], 0, v[162:163]
	s_add_i32 m0, s63, 0x2000
	s_nop 0
	global_load_lds_dwordx4 v[48:49], off
	s_waitcnt vmcnt(6)
	s_barrier
	v_mfma_f32_16x16x32_bf16 v[28:31], v[198:201], v[112:115], v[28:31]
	v_mfma_f32_16x16x32_bf16 v[24:27], v[190:193], v[120:123], v[24:27]
	v_mfma_f32_16x16x32_bf16 v[12:15], v[198:201], v[120:123], v[12:15]
	v_mfma_f32_16x16x32_bf16 v[20:23], v[190:193], v[174:177], v[20:23]
	v_mfma_f32_16x16x32_bf16 v[4:7], v[198:201], v[174:177], v[4:7]
	v_mfma_f32_16x16x32_bf16 v[32:35], v[190:193], v[182:185], v[32:35]
	v_mfma_f32_16x16x32_bf16 v[0:3], v[198:201], v[182:185], v[0:3]
	v_mfma_f32_16x16x32_bf16 v[48:51], v[190:193], v[112:115], v[84:87]
	v_mfma_f32_16x16x32_bf16 v[28:31], v[202:205], v[116:119], v[28:31]
	v_mfma_f32_16x16x32_bf16 v[24:27], v[194:197], v[124:127], v[24:27]
	v_mfma_f32_16x16x32_bf16 v[12:15], v[202:205], v[124:127], v[12:15]
	v_mfma_f32_16x16x32_bf16 v[20:23], v[194:197], v[178:181], v[20:23]
	v_mfma_f32_16x16x32_bf16 v[4:7], v[202:205], v[178:181], v[4:7]
	v_mfma_f32_16x16x32_bf16 v[32:35], v[194:197], v[186:189], v[32:35]
	v_mfma_f32_16x16x32_bf16 v[0:3], v[202:205], v[186:189], v[0:3]
	v_mfma_f32_16x16x32_bf16 v[48:51], v[194:197], v[116:119], v[48:51]
	s_add_i32 s63, 0, 0x18000
	v_add_u32_e32 v64, s63, v232
	s_barrier
	ds_read_b128 v[52:55], v64
	ds_read_b128 v[56:59], v64 offset:1024
	ds_read_b128 v[84:87], v64 offset:2048
	ds_read_b128 v[174:177], v64 offset:3072
	s_add_u32 s60, s90, 0x40000
	s_addc_u32 s61, s91, 0
	s_mov_b32 m0, s14
	v_lshl_add_u64 v[120:121], s[60:61], 0, v[160:161]
	ds_read_b128 v[64:67], v237 offset:32768
	ds_read_b128 v[112:115], v237 offset:33792
	ds_read_b128 v[116:119], v237 offset:34816
	ds_read_b128 v[178:181], v237 offset:35840
	ds_read_b128 v[182:185], v237 offset:36864
	ds_read_b128 v[186:189], v237 offset:37888
	ds_read_b128 v[190:193], v237 offset:38912
	ds_read_b128 v[194:197], v237 offset:39936
	global_load_lds_dwordx4 v[120:121], off
	v_lshl_add_u64 v[120:121], s[60:61], 0, v[162:163]
	s_mov_b32 m0, s15
	s_nop 0
	global_load_lds_dwordx4 v[120:121], off
	s_waitcnt lgkmcnt(8)
	s_barrier
	s_waitcnt lgkmcnt(0)
	s_waitcnt lgkmcnt(0)
	v_mfma_f32_16x16x32_bf16 v[120:123], v[52:55], v[64:67], v[156:159]
	v_mfma_f32_16x16x32_bf16 v[156:159], v[56:59], v[112:115], v[120:123]
	v_mfma_f32_16x16x32_bf16 v[120:123], v[84:87], v[64:67], v[132:135]
	v_mfma_f32_16x16x32_bf16 v[132:135], v[174:177], v[112:115], v[120:123]
	v_mfma_f32_16x16x32_bf16 v[120:123], v[52:55], v[116:119], v[152:155]
	v_mfma_f32_16x16x32_bf16 v[152:155], v[56:59], v[178:181], v[120:123]
	v_mfma_f32_16x16x32_bf16 v[120:123], v[84:87], v[116:119], v[128:131]
	v_mfma_f32_16x16x32_bf16 v[128:131], v[174:177], v[178:181], v[120:123]
	v_mfma_f32_16x16x32_bf16 v[120:123], v[52:55], v[182:185], v[140:143]
	v_mfma_f32_16x16x32_bf16 v[140:143], v[56:59], v[186:189], v[120:123]
	v_mfma_f32_16x16x32_bf16 v[104:107], v[84:87], v[182:185], v[104:107]
	v_mfma_f32_16x16x32_bf16 v[120:123], v[52:55], v[190:193], v[144:147]
	v_mfma_f32_16x16x32_bf16 v[108:111], v[84:87], v[190:193], v[108:111]
	v_mfma_f32_16x16x32_bf16 v[104:107], v[174:177], v[186:189], v[104:107]
	v_mfma_f32_16x16x32_bf16 v[144:147], v[56:59], v[194:197], v[120:123]
	v_mfma_f32_16x16x32_bf16 v[108:111], v[174:177], v[194:197], v[108:111]
	s_barrier
	s_add_i32 s60, 0, 0x1c000
	s_nop 0
	v_add_u32_e32 v120, s60, v232
	s_add_i32 s61, s63, s11
	ds_read_b128 v[198:201], v120
	ds_read_b128 v[202:205], v120 offset:1024
	ds_read_b128 v[206:209], v120 offset:2048
	ds_read_b128 v[210:213], v120 offset:3072
	v_lshl_add_u64 v[120:121], v[214:215], 0, s[52:53]
	s_mov_b32 m0, s61
	s_nop 0
	global_load_lds_dwordx4 v[120:121], off
	v_lshl_add_u64 v[120:121], v[216:217], 0, s[52:53]
	s_add_i32 m0, s61, 0x2000
	s_nop 0
	global_load_lds_dwordx4 v[120:121], off
	s_barrier
	s_waitcnt lgkmcnt(0)
	s_waitcnt lgkmcnt(0)
	v_mfma_f32_16x16x32_bf16 v[120:123], v[198:201], v[64:67], v[148:151]
	v_mfma_f32_16x16x32_bf16 v[64:67], v[206:209], v[64:67], v[68:71]
	v_mfma_f32_16x16x32_bf16 v[124:127], v[210:213], v[112:115], v[64:67]
	v_mfma_f32_16x16x32_bf16 v[64:67], v[198:201], v[116:119], v[72:75]
	v_mfma_f32_16x16x32_bf16 v[148:151], v[202:205], v[112:115], v[120:123]
	v_mfma_f32_16x16x32_bf16 v[120:123], v[202:205], v[178:181], v[64:67]
	v_mfma_f32_16x16x32_bf16 v[64:67], v[206:209], v[116:119], v[76:79]
	v_mfma_f32_16x16x32_bf16 v[112:115], v[210:213], v[178:181], v[64:67]
	v_mfma_f32_16x16x32_bf16 v[64:67], v[198:201], v[182:185], v[80:83]
	v_mfma_f32_16x16x32_bf16 v[116:119], v[202:205], v[186:189], v[64:67]
	v_mfma_f32_16x16x32_bf16 v[64:67], v[206:209], v[182:185], v[100:103]
	v_mfma_f32_16x16x32_bf16 v[100:103], v[210:213], v[186:189], v[64:67]
	v_mfma_f32_16x16x32_bf16 v[64:67], v[198:201], v[190:193], v[136:139]
	v_mfma_f32_16x16x32_bf16 v[136:139], v[202:205], v[194:197], v[64:67]
	v_mfma_f32_16x16x32_bf16 v[64:67], v[206:209], v[190:193], v[96:99]
	v_mfma_f32_16x16x32_bf16 v[96:99], v[210:213], v[194:197], v[64:67]
	s_mov_b32 m0, s17
	s_nop 4
	v_lshl_add_u64 v[64:65], v[218:219], 0, s[52:53]
	s_barrier
	ds_read_b128 v[68:71], v237 offset:49152
	ds_read_b128 v[72:75], v237 offset:50176
	ds_read_b128 v[76:79], v237 offset:51200
	ds_read_b128 v[80:83], v237 offset:52224
	ds_read_b128 v[178:181], v237 offset:53248
	ds_read_b128 v[182:185], v237 offset:54272
	ds_read_b128 v[186:189], v237 offset:55296
	ds_read_b128 v[190:193], v237 offset:56320
	global_load_lds_dwordx4 v[64:65], off
	v_lshl_add_u64 v[64:65], v[220:221], 0, s[52:53]
	s_mov_b32 m0, s18
	s_nop 0
	global_load_lds_dwordx4 v[64:65], off
	s_barrier
	s_waitcnt lgkmcnt(0)
	s_waitcnt lgkmcnt(0)
	v_mfma_f32_16x16x32_bf16 v[64:67], v[52:55], v[68:71], v[92:95]
	v_mfma_f32_16x16x32_bf16 v[92:95], v[56:59], v[72:75], v[64:67]
	v_mfma_f32_16x16x32_bf16 v[40:43], v[84:87], v[68:71], v[40:43]
	v_mfma_f32_16x16x32_bf16 v[64:67], v[52:55], v[76:79], v[88:91]
	v_mfma_f32_16x16x32_bf16 v[36:39], v[84:87], v[76:79], v[36:39]
	v_mfma_f32_16x16x32_bf16 v[60:63], v[52:55], v[178:181], v[60:63]
	v_mfma_f32_16x16x32_bf16 v[8:11], v[84:87], v[178:181], v[8:11]
	v_mfma_f32_16x16x32_bf16 v[44:47], v[52:55], v[186:189], v[44:47]
	v_mfma_f32_16x16x32_bf16 v[16:19], v[84:87], v[186:189], v[16:19]
	v_mfma_f32_16x16x32_bf16 v[40:43], v[174:177], v[72:75], v[40:43]
	v_mfma_f32_16x16x32_bf16 v[88:91], v[56:59], v[80:83], v[64:67]
	v_mfma_f32_16x16x32_bf16 v[36:39], v[174:177], v[80:83], v[36:39]
	v_mfma_f32_16x16x32_bf16 v[60:63], v[56:59], v[182:185], v[60:63]
	v_mfma_f32_16x16x32_bf16 v[8:11], v[174:177], v[182:185], v[8:11]
	v_mfma_f32_16x16x32_bf16 v[64:67], v[56:59], v[190:193], v[44:47]
	v_mfma_f32_16x16x32_bf16 v[16:19], v[174:177], v[190:193], v[16:19]
	s_barrier
	s_add_u32 s0, s0, 0x40080
	s_addc_u32 s1, s1, 0
	s_add_i32 s60, s60, s11
	v_lshl_add_u64 v[44:45], s[0:1], 0, v[160:161]
	s_mov_b32 m0, s60
	s_nop 0
	global_load_lds_dwordx4 v[44:45], off
	v_lshl_add_u64 v[44:45], s[0:1], 0, v[162:163]
	s_add_i32 m0, s60, 0x2000
	s_nop 0
	global_load_lds_dwordx4 v[44:45], off
	s_waitcnt vmcnt(6)
	s_barrier
	v_mfma_f32_16x16x32_bf16 v[44:47], v[198:201], v[68:71], v[48:51]
	v_mfma_f32_16x16x32_bf16 v[28:31], v[206:209], v[68:71], v[28:31]
	v_mfma_f32_16x16x32_bf16 v[24:27], v[198:201], v[76:79], v[24:27]
	v_mfma_f32_16x16x32_bf16 v[12:15], v[206:209], v[76:79], v[12:15]
	v_mfma_f32_16x16x32_bf16 v[20:23], v[198:201], v[178:181], v[20:23]
	v_mfma_f32_16x16x32_bf16 v[4:7], v[206:209], v[178:181], v[4:7]
	v_mfma_f32_16x16x32_bf16 v[32:35], v[198:201], v[186:189], v[32:35]
	v_mfma_f32_16x16x32_bf16 v[0:3], v[206:209], v[186:189], v[0:3]
	v_mfma_f32_16x16x32_bf16 v[84:87], v[202:205], v[72:75], v[44:47]
	v_mfma_f32_16x16x32_bf16 v[28:31], v[210:213], v[72:75], v[28:31]
	v_mfma_f32_16x16x32_bf16 v[24:27], v[202:205], v[80:83], v[24:27]
	v_mfma_f32_16x16x32_bf16 v[12:15], v[210:213], v[80:83], v[12:15]
	v_mfma_f32_16x16x32_bf16 v[20:23], v[202:205], v[182:185], v[20:23]
	v_mfma_f32_16x16x32_bf16 v[4:7], v[210:213], v[182:185], v[4:7]
	v_mfma_f32_16x16x32_bf16 v[32:35], v[202:205], v[190:193], v[32:35]
	v_mfma_f32_16x16x32_bf16 v[0:3], v[210:213], v[190:193], v[0:3]
	s_add_i32 s59, s59, 2
	s_add_u32 vcc_lo, vcc_lo, 0x100
	s_addc_u32 vcc_hi, vcc_hi, 0
	s_add_u32 s55, s55, 0x100
	s_addc_u32 s57, s57, 0
	s_cmp_gt_u32 s59, 13
	s_barrier
	s_cbranch_scc0 .LBB0_703
	s_cmpk_gt_u32 s5, 0xff
	s_cbranch_scc1 .Lepi0_ffnin
	s_barrier
.Lepi0_ffnin:
	v_lshl_add_u32 v164, s84, 8, v231
	v_lshl_add_u64 v[44:45], v[164:165], 2, s[34:35]
	global_load_dword v184, v[44:45], off
	v_or_b32_e32 v182, 16, v164
	v_mov_b32_e32 v183, v165
	v_lshl_add_u64 v[44:45], v[182:183], 2, s[34:35]
	global_load_dword v186, v[44:45], off
	v_or_b32_e32 v44, 32, v164
	v_mov_b32_e32 v45, v165
	v_lshl_add_u64 v[44:45], v[44:45], 2, s[34:35]
	v_or_b32_e32 v180, 48, v164
	v_mov_b32_e32 v181, v165
	global_load_dword v200, v[44:45], off
	v_lshl_add_u64 v[44:45], v[180:181], 2, s[34:35]
	v_add_u32_e32 v178, 0x80, v164
	v_mov_b32_e32 v179, v165
	global_load_dword v185, v[44:45], off
	v_lshl_add_u64 v[44:45], v[178:179], 2, s[34:35]
	v_add_u32_e32 v174, 0x90, v164
	v_mov_b32_e32 v175, v165
	global_load_dword v183, v[44:45], off
	v_lshl_add_u64 v[44:45], v[174:175], 2, s[34:35]
	global_load_dword v181, v[44:45], off
	v_add_u32_e32 v44, 0xa0, v164
	v_mov_b32_e32 v45, v165
	v_lshl_add_u64 v[44:45], v[44:45], 2, s[34:35]
	global_load_dword v175, v[44:45], off
	v_add_u32_e32 v44, 0xb0, v164
	v_mov_b32_e32 v45, v165
	v_lshl_or_b32 v176, s88, 7, v235
	v_lshl_add_u64 v[44:45], v[44:45], 2, s[34:35]
	v_ashrrev_i32_e32 v177, 31, v176
	v_readlane_b32 s44, v254, 1
	global_load_dword v179, v[44:45], off
	v_lshlrev_b64 v[44:45], 2, v[176:177]
	v_readlane_b32 s48, v254, 5
	v_readlane_b32 s49, v254, 6
	v_readlane_b32 s50, v254, 7
	v_readlane_b32 s51, v254, 8
	v_lshl_add_u64 v[48:49], s[48:49], 0, v[44:45]
	v_lshl_add_u64 v[52:53], s[96:97], 0, v[44:45]
	v_lshl_add_u64 v[56:57], s[86:87], 0, v[44:45]
	v_lshl_add_u64 v[80:81], s[50:51], 0, v[44:45]
	global_load_dwordx4 v[44:47], v[48:49], off offset:16
	global_load_dwordx4 v[68:71], v[48:49], off
	s_nop 0
	global_load_dwordx4 v[48:51], v[52:53], off offset:16
	global_load_dwordx4 v[72:75], v[52:53], off
	s_nop 0
	global_load_dwordx4 v[52:55], v[56:57], off offset:16
	global_load_dwordx4 v[76:79], v[56:57], off
	s_nop 0
	global_load_dwordx4 v[56:59], v[80:81], off offset:16
	s_nop 0
	global_load_dwordx4 v[80:83], v[80:81], off
	v_mov_b32_e32 v190, 0
	v_mov_b32_e32 v192, 0
	v_mov_b32_e32 v191, 0
	v_mov_b32_e32 v193, 0
	v_mov_b32_e32 v196, 0
	s_lshl_b32 s3, s84, 2
	v_mov_b32_e32 v198, 0
	s_add_i32 s3, s3, s10
	v_mov_b32_e32 v197, 0
	s_mul_i32 s51, s3, 6
	v_mov_b32_e32 v199, 0
	v_readlane_b32 s45, v254, 2
	v_readlane_b32 s46, v254, 3
	v_readlane_b32 s47, v254, 4
	s_waitcnt vmcnt(0)
	v_fmamk_f32 v177, v184, 0x3a800000, v239
	v_cmp_gt_f32_e32 vcc, s33, v177
	v_mul_f32_e32 v184, 0x4b800000, v177
	s_nop 0
	v_cndmask_b32_e32 v177, v177, v184, vcc
	v_rsq_f32_e32 v177, v177
	s_nop 0
	v_mul_f32_e32 v184, 0x45800000, v177
	v_cndmask_b32_e32 v188, v177, v184, vcc
	v_fmamk_f32 v177, v186, 0x3a800000, v239
	v_cmp_gt_f32_e32 vcc, s33, v177
	v_mul_f32_e32 v184, 0x4b800000, v177
	v_pk_mul_f32 v[186:187], v[156:157], v[188:189] op_sel_hi:[1,0]
	v_cndmask_b32_e32 v177, v177, v184, vcc
	v_rsq_f32_e32 v177, v177
	v_cndmask_b32_e64 v156, v186, 0, s[38:39]
	v_pk_mul_f32 v[194:195], v[158:159], v[188:189] op_sel_hi:[1,0]
	v_mul_f32_e32 v184, 0x45800000, v177
	v_cndmask_b32_e32 v184, v177, v184, vcc
	v_mov_b32_dpp v190, v156 row_ror:1 row_mask:0xf bank_mask:0xf
	v_pk_mul_f32 v[156:157], v[152:153], v[184:185] op_sel_hi:[1,0]
	v_pk_mul_f32 v[158:159], v[154:155], v[184:185] op_sel_hi:[1,0]
	v_cndmask_b32_e64 v152, v186, v156, s[42:43]
	v_add_u32_e32 v155, s51, v234
	s_nop 0
	v_mov_b32_dpp v192, v152 row_ror:15 row_mask:0xf bank_mask:0xf
	v_cndmask_b32_e64 v152, v187, 0, s[38:39]
	s_nop 1
	v_mov_b32_dpp v191, v152 row_ror:1 row_mask:0xf bank_mask:0xf
	v_cndmask_b32_e64 v152, v187, v157, s[42:43]
	s_nop 1
	v_mov_b32_dpp v193, v152 row_ror:15 row_mask:0xf bank_mask:0xf
	v_cndmask_b32_e64 v152, v194, 0, s[38:39]
	s_nop 1
	v_mov_b32_dpp v196, v152 row_ror:1 row_mask:0xf bank_mask:0xf
	v_cndmask_b32_e64 v152, v194, v158, s[42:43]
	s_nop 1
	v_mov_b32_dpp v198, v152 row_ror:15 row_mask:0xf bank_mask:0xf
	v_cndmask_b32_e64 v152, v195, 0, s[38:39]
	s_nop 1
	v_mov_b32_dpp v197, v152 row_ror:1 row_mask:0xf bank_mask:0xf
	v_cndmask_b32_e64 v152, v195, v159, s[42:43]
	s_nop 1
	v_mov_b32_dpp v199, v152 row_ror:15 row_mask:0xf bank_mask:0xf
	s_and_saveexec_b64 s[0:1], s[70:71]
	s_cbranch_execz .LBB0_706
	v_mad_u64_u32 v[202:203], s[22:23], v155, s65, v[176:177]
	v_mov_b32_e32 v203, v165
	v_cvt_pk_bf16_f32 v152, v186, v187
	v_cvt_pk_bf16_f32 v153, v194, v195
	v_lshl_add_u64 v[202:203], v[202:203], 1, s[30:31]
	global_store_dwordx2 v[202:203], v[152:153], off

.LBB0_868:
	s_cmp_lt_i32 s82, 14
	s_cselect_b64 s[0:1], -1, 0
	s_and_b64 s[0:1], s[0:1], s[2:3]
	s_andn2_b64 vcc, exec, s[0:1]
	s_cbranch_vccnz .LBB0_893
	s_mov_b64 s[0:1], 0
	v_readlane_b32 s2, v254, 0
	v_mov_b32_e32 v0, v230
	s_cmpk_gt_i32 s2, 0x3ff
	v_readfirstlane_b32 s16, v230
	s_cbranch_scc1 .LBB0_893
	s_mov_b32 s41, s2
	s_ashr_i32 s17, s41, 31
	s_lshr_b32 s2, s17, 29
	s_add_i32 s4, s41, s2
	s_and_b32 s2, s4, -8
	s_sub_i32 s6, s41, s2
	s_cmp_gt_i32 s6, -1
	s_cbranch_scc0 .LBB0_872
	s_lshl_b32 s7, s6, 7
	s_ashr_i32 s2, s4, 3
	s_cbranch_execz .LBB0_873
	s_branch .LBB0_874
	s_nop 0
	s_nop 0
	s_nop 0
	s_nop 0
	s_nop 0
	s_nop 0
	s_nop 0
	s_nop 0
	s_nop 0
	s_nop 0
	s_nop 0
	s_nop 0
	s_nop 0

.LBB0_888:
	ds_read_b128 v[140:143], v149
	ds_read_b128 v[152:155], v149 offset:1024
	ds_read_b128 v[156:159], v149 offset:2048
	ds_read_b128 v[160:163], v149 offset:3072
	s_add_u32 s10, s2, 0x100
	s_addc_u32 s11, s3, 0
	s_cmp_eq_u32 s39, 40
	s_cselect_b32 s15, s7, s11
	s_cselect_b32 s14, s6, s10
	s_cselect_b32 s13, s5, s38
	s_cselect_b32 s12, s4, s37
	v_lshl_add_u64 v[144:145], s[2:3], 0, v[132:133]
	s_add_i32 m0, s23, 0xc000
	ds_read_b128 v[164:167], v150
	ds_read_b128 v[168:171], v150 offset:1024
	ds_read_b128 v[172:175], v150 offset:2048
	ds_read_b128 v[176:179], v150 offset:3072
	ds_read_b128 v[180:183], v150 offset:4096
	ds_read_b128 v[184:187], v150 offset:5120
	ds_read_b128 v[188:191], v150 offset:6144
	ds_read_b128 v[192:195], v150 offset:7168
	global_load_lds_dwordx4 v[144:145], off
	v_lshl_add_u64 v[144:145], s[2:3], 0, v[134:135]
	s_add_i32 m0, s23, 0xe000
	s_nop 0
	global_load_lds_dwordx4 v[144:145], off
	s_waitcnt lgkmcnt(8)
	s_barrier
	s_waitcnt lgkmcnt(0)
	s_waitcnt lgkmcnt(0)
	v_mfma_f32_16x16x32_bf16 v[124:127], v[140:143], v[164:167], v[124:127]
	v_mfma_f32_16x16x32_bf16 v[120:123], v[156:159], v[164:167], v[120:123]
	v_mfma_f32_16x16x32_bf16 v[116:119], v[140:143], v[172:175], v[116:119]
	v_mfma_f32_16x16x32_bf16 v[112:115], v[156:159], v[172:175], v[112:115]
	v_mfma_f32_16x16x32_bf16 v[92:95], v[140:143], v[180:183], v[92:95]
	v_mfma_f32_16x16x32_bf16 v[88:91], v[156:159], v[180:183], v[88:91]
	v_mfma_f32_16x16x32_bf16 v[84:87], v[140:143], v[188:191], v[84:87]
	v_mfma_f32_16x16x32_bf16 v[80:83], v[156:159], v[188:191], v[80:83]
	v_mfma_f32_16x16x32_bf16 v[124:127], v[152:155], v[168:171], v[124:127]
	v_mfma_f32_16x16x32_bf16 v[120:123], v[160:163], v[168:171], v[120:123]
	v_mfma_f32_16x16x32_bf16 v[116:119], v[152:155], v[176:179], v[116:119]
	v_mfma_f32_16x16x32_bf16 v[112:115], v[160:163], v[176:179], v[112:115]
	v_mfma_f32_16x16x32_bf16 v[92:95], v[152:155], v[184:187], v[92:95]
	v_mfma_f32_16x16x32_bf16 v[88:91], v[160:163], v[184:187], v[88:91]
	v_mfma_f32_16x16x32_bf16 v[84:87], v[152:155], v[192:195], v[84:87]
	v_mfma_f32_16x16x32_bf16 v[80:83], v[160:163], v[192:195], v[80:83]
	s_barrier
	s_add_i32 s2, s30, s22
	v_lshl_add_u64 v[144:145], s[12:13], 0, v[128:129]
	s_mov_b32 m0, s2
	ds_read_b128 v[196:199], v151
	ds_read_b128 v[200:203], v151 offset:1024
	ds_read_b128 v[204:207], v151 offset:2048
	ds_read_b128 v[208:211], v151 offset:3072
	global_load_lds_dwordx4 v[144:145], off
	v_lshl_add_u64 v[212:213], s[12:13], 0, v[130:131]
	s_add_i32 m0, s2, 0x2000
	s_nop 0
	global_load_lds_dwordx4 v[212:213], off
	s_barrier
	s_waitcnt lgkmcnt(0)
	s_waitcnt lgkmcnt(0)
	v_mfma_f32_16x16x32_bf16 v[108:111], v[196:199], v[164:167], v[108:111]
	v_mfma_f32_16x16x32_bf16 v[104:107], v[204:207], v[164:167], v[104:107]
	v_mfma_f32_16x16x32_bf16 v[100:103], v[196:199], v[172:175], v[100:103]
	v_mfma_f32_16x16x32_bf16 v[96:99], v[204:207], v[172:175], v[96:99]
	v_mfma_f32_16x16x32_bf16 v[76:79], v[196:199], v[180:183], v[76:79]
	v_mfma_f32_16x16x32_bf16 v[72:75], v[204:207], v[180:183], v[72:75]
	v_mfma_f32_16x16x32_bf16 v[68:71], v[196:199], v[188:191], v[68:71]
	v_mfma_f32_16x16x32_bf16 v[64:67], v[204:207], v[188:191], v[64:67]
	v_mfma_f32_16x16x32_bf16 v[108:111], v[200:203], v[168:171], v[108:111]
	v_mfma_f32_16x16x32_bf16 v[104:107], v[208:211], v[168:171], v[104:107]
	v_mfma_f32_16x16x32_bf16 v[100:103], v[200:203], v[176:179], v[100:103]
	v_mfma_f32_16x16x32_bf16 v[96:99], v[208:211], v[176:179], v[96:99]
	v_mfma_f32_16x16x32_bf16 v[76:79], v[200:203], v[184:187], v[76:79]
	v_mfma_f32_16x16x32_bf16 v[72:75], v[208:211], v[184:187], v[72:75]
	v_mfma_f32_16x16x32_bf16 v[68:71], v[200:203], v[192:195], v[68:71]
	v_mfma_f32_16x16x32_bf16 v[64:67], v[208:211], v[192:195], v[64:67]
	s_mov_b32 m0, s23
	v_lshl_add_u64 v[214:215], s[14:15], 0, v[128:129]
	s_barrier
	ds_read_b128 v[164:167], v150 offset:16384
	ds_read_b128 v[168:171], v150 offset:17408
	ds_read_b128 v[172:175], v150 offset:18432
	ds_read_b128 v[176:179], v150 offset:19456
	ds_read_b128 v[180:183], v150 offset:20480
	ds_read_b128 v[184:187], v150 offset:21504
	ds_read_b128 v[188:191], v150 offset:22528
	ds_read_b128 v[192:195], v150 offset:23552
	global_load_lds_dwordx4 v[214:215], off
	v_lshl_add_u64 v[216:217], s[14:15], 0, v[130:131]
	s_mov_b32 m0, s24
	s_nop 0
	global_load_lds_dwordx4 v[216:217], off
	s_barrier
	s_waitcnt lgkmcnt(0)
	s_waitcnt lgkmcnt(0)
	v_mfma_f32_16x16x32_bf16 v[60:63], v[140:143], v[164:167], v[60:63]
	v_mfma_f32_16x16x32_bf16 v[56:59], v[156:159], v[164:167], v[56:59]
	v_mfma_f32_16x16x32_bf16 v[52:55], v[140:143], v[172:175], v[52:55]
	v_mfma_f32_16x16x32_bf16 v[48:51], v[156:159], v[172:175], v[48:51]
	v_mfma_f32_16x16x32_bf16 v[28:31], v[140:143], v[180:183], v[28:31]
	v_mfma_f32_16x16x32_bf16 v[24:27], v[156:159], v[180:183], v[24:27]
	v_mfma_f32_16x16x32_bf16 v[16:19], v[140:143], v[188:191], v[16:19]
	v_mfma_f32_16x16x32_bf16 v[8:11], v[156:159], v[188:191], v[8:11]
	v_mfma_f32_16x16x32_bf16 v[60:63], v[152:155], v[168:171], v[60:63]
	v_mfma_f32_16x16x32_bf16 v[56:59], v[160:163], v[168:171], v[56:59]
	v_mfma_f32_16x16x32_bf16 v[52:55], v[152:155], v[176:179], v[52:55]
	v_mfma_f32_16x16x32_bf16 v[48:51], v[160:163], v[176:179], v[48:51]
	v_mfma_f32_16x16x32_bf16 v[28:31], v[152:155], v[184:187], v[28:31]
	v_mfma_f32_16x16x32_bf16 v[24:27], v[160:163], v[184:187], v[24:27]
	v_mfma_f32_16x16x32_bf16 v[16:19], v[152:155], v[192:195], v[16:19]
	v_mfma_f32_16x16x32_bf16 v[8:11], v[160:163], v[192:195], v[8:11]
	s_barrier
	s_add_u32 s2, s12, 0xb0000
	s_addc_u32 s3, s13, 0
	s_add_i32 s40, s31, s22
	v_lshl_add_u64 v[140:141], s[2:3], 0, v[128:129]
	s_mov_b32 m0, s40
	s_nop 0
	global_load_lds_dwordx4 v[140:141], off
	v_lshl_add_u64 v[140:141], s[2:3], 0, v[130:131]
	s_add_i32 m0, s40, 0x2000
	s_nop 0
	global_load_lds_dwordx4 v[140:141], off
	s_waitcnt vmcnt(6)
	s_barrier
	v_mfma_f32_16x16x32_bf16 v[44:47], v[196:199], v[164:167], v[44:47]
	v_mfma_f32_16x16x32_bf16 v[40:43], v[204:207], v[164:167], v[40:43]
	v_mfma_f32_16x16x32_bf16 v[36:39], v[196:199], v[172:175], v[36:39]
	v_mfma_f32_16x16x32_bf16 v[32:35], v[204:207], v[172:175], v[32:35]
	v_mfma_f32_16x16x32_bf16 v[20:23], v[196:199], v[180:183], v[20:23]
	v_mfma_f32_16x16x32_bf16 v[12:15], v[204:207], v[180:183], v[12:15]
	v_mfma_f32_16x16x32_bf16 v[4:7], v[196:199], v[188:191], v[4:7]
	v_mfma_f32_16x16x32_bf16 v[0:3], v[204:207], v[188:191], v[0:3]
	v_mfma_f32_16x16x32_bf16 v[44:47], v[200:203], v[168:171], v[44:47]
	v_mfma_f32_16x16x32_bf16 v[40:43], v[208:211], v[168:171], v[40:43]
	v_mfma_f32_16x16x32_bf16 v[36:39], v[200:203], v[176:179], v[36:39]
	v_mfma_f32_16x16x32_bf16 v[32:35], v[208:211], v[176:179], v[32:35]
	v_mfma_f32_16x16x32_bf16 v[20:23], v[200:203], v[184:187], v[20:23]
	v_mfma_f32_16x16x32_bf16 v[12:15], v[208:211], v[184:187], v[12:15]
	v_mfma_f32_16x16x32_bf16 v[4:7], v[200:203], v[192:195], v[4:7]
	v_mfma_f32_16x16x32_bf16 v[0:3], v[208:211], v[192:195], v[0:3]
	s_add_i32 s40, 0, 0x18000
	v_add_u32_e32 v160, s40, v147
	s_barrier
	ds_read_b128 v[140:143], v160
	ds_read_b128 v[152:155], v160 offset:1024
	ds_read_b128 v[156:159], v160 offset:2048
	ds_read_b128 v[160:163], v160 offset:3072
	s_add_u32 s2, s14, 0xb0000
	s_addc_u32 s3, s15, 0
	s_mov_b32 m0, s25
	v_lshl_add_u64 v[196:197], s[2:3], 0, v[128:129]
	ds_read_b128 v[164:167], v150 offset:32768
	ds_read_b128 v[168:171], v150 offset:33792
	ds_read_b128 v[172:175], v150 offset:34816
	ds_read_b128 v[176:179], v150 offset:35840
	ds_read_b128 v[180:183], v150 offset:36864
	ds_read_b128 v[184:187], v150 offset:37888
	ds_read_b128 v[188:191], v150 offset:38912
	ds_read_b128 v[192:195], v150 offset:39936
	global_load_lds_dwordx4 v[196:197], off
	v_lshl_add_u64 v[196:197], s[2:3], 0, v[130:131]
	s_mov_b32 m0, s26
	s_nop 0
	global_load_lds_dwordx4 v[196:197], off
	s_waitcnt lgkmcnt(8)
	s_barrier
	s_waitcnt lgkmcnt(0)
	s_waitcnt lgkmcnt(0)
	v_mfma_f32_16x16x32_bf16 v[124:127], v[140:143], v[164:167], v[124:127]
	v_mfma_f32_16x16x32_bf16 v[120:123], v[156:159], v[164:167], v[120:123]
	v_mfma_f32_16x16x32_bf16 v[116:119], v[140:143], v[172:175], v[116:119]
	v_mfma_f32_16x16x32_bf16 v[112:115], v[156:159], v[172:175], v[112:115]
	v_mfma_f32_16x16x32_bf16 v[92:95], v[140:143], v[180:183], v[92:95]
	v_mfma_f32_16x16x32_bf16 v[88:91], v[156:159], v[180:183], v[88:91]
	v_mfma_f32_16x16x32_bf16 v[84:87], v[140:143], v[188:191], v[84:87]
	v_mfma_f32_16x16x32_bf16 v[80:83], v[156:159], v[188:191], v[80:83]
	v_mfma_f32_16x16x32_bf16 v[124:127], v[152:155], v[168:171], v[124:127]
	v_mfma_f32_16x16x32_bf16 v[120:123], v[160:163], v[168:171], v[120:123]
	v_mfma_f32_16x16x32_bf16 v[116:119], v[152:155], v[176:179], v[116:119]
	v_mfma_f32_16x16x32_bf16 v[112:115], v[160:163], v[176:179], v[112:115]
	v_mfma_f32_16x16x32_bf16 v[92:95], v[152:155], v[184:187], v[92:95]
	v_mfma_f32_16x16x32_bf16 v[88:91], v[160:163], v[184:187], v[88:91]
	v_mfma_f32_16x16x32_bf16 v[84:87], v[152:155], v[192:195], v[84:87]
	v_mfma_f32_16x16x32_bf16 v[80:83], v[160:163], v[192:195], v[80:83]
	s_barrier
	s_add_i32 s14, 0, 0x1c000
	s_add_i32 s2, s40, s22
	v_add_u32_e32 v208, s14, v147
	v_lshl_add_u64 v[144:145], v[144:145], 0, s[8:9]
	s_mov_b32 m0, s2
	ds_read_b128 v[196:199], v208
	ds_read_b128 v[200:203], v208 offset:1024
	ds_read_b128 v[204:207], v208 offset:2048
	ds_read_b128 v[208:211], v208 offset:3072
	global_load_lds_dwordx4 v[144:145], off
	v_lshl_add_u64 v[144:145], v[212:213], 0, s[8:9]
	s_add_i32 m0, s2, 0x2000
	s_nop 0
	global_load_lds_dwordx4 v[144:145], off
	s_barrier
	s_waitcnt lgkmcnt(0)
	s_waitcnt lgkmcnt(0)
	v_mfma_f32_16x16x32_bf16 v[108:111], v[196:199], v[164:167], v[108:111]
	v_mfma_f32_16x16x32_bf16 v[104:107], v[204:207], v[164:167], v[104:107]
	v_mfma_f32_16x16x32_bf16 v[100:103], v[196:199], v[172:175], v[100:103]
	v_mfma_f32_16x16x32_bf16 v[96:99], v[204:207], v[172:175], v[96:99]
	v_mfma_f32_16x16x32_bf16 v[76:79], v[196:199], v[180:183], v[76:79]
	v_mfma_f32_16x16x32_bf16 v[72:75], v[204:207], v[180:183], v[72:75]
	v_mfma_f32_16x16x32_bf16 v[68:71], v[196:199], v[188:191], v[68:71]
	v_mfma_f32_16x16x32_bf16 v[64:67], v[204:207], v[188:191], v[64:67]
	v_mfma_f32_16x16x32_bf16 v[108:111], v[200:203], v[168:171], v[108:111]
	v_mfma_f32_16x16x32_bf16 v[104:107], v[208:211], v[168:171], v[104:107]
	v_mfma_f32_16x16x32_bf16 v[100:103], v[200:203], v[176:179], v[100:103]
	v_mfma_f32_16x16x32_bf16 v[96:99], v[208:211], v[176:179], v[96:99]
	v_mfma_f32_16x16x32_bf16 v[76:79], v[200:203], v[184:187], v[76:79]
	v_mfma_f32_16x16x32_bf16 v[72:75], v[208:211], v[184:187], v[72:75]
	v_mfma_f32_16x16x32_bf16 v[68:71], v[200:203], v[192:195], v[68:71]
	v_mfma_f32_16x16x32_bf16 v[64:67], v[208:211], v[192:195], v[64:67]
	s_mov_b32 m0, s28
	v_lshl_add_u64 v[144:145], v[214:215], 0, s[8:9]
	s_barrier
	ds_read_b128 v[164:167], v150 offset:49152
	ds_read_b128 v[168:171], v150 offset:50176
	ds_read_b128 v[172:175], v150 offset:51200
	ds_read_b128 v[176:179], v150 offset:52224
	ds_read_b128 v[180:183], v150 offset:53248
	ds_read_b128 v[184:187], v150 offset:54272
	ds_read_b128 v[188:191], v150 offset:55296
	ds_read_b128 v[192:195], v150 offset:56320
	global_load_lds_dwordx4 v[144:145], off
	v_lshl_add_u64 v[144:145], v[216:217], 0, s[8:9]
	s_mov_b32 m0, s29
	s_nop 0
	global_load_lds_dwordx4 v[144:145], off
	s_barrier
	s_waitcnt lgkmcnt(0)
	s_waitcnt lgkmcnt(0)
	v_mfma_f32_16x16x32_bf16 v[60:63], v[140:143], v[164:167], v[60:63]
	v_mfma_f32_16x16x32_bf16 v[56:59], v[156:159], v[164:167], v[56:59]
	v_mfma_f32_16x16x32_bf16 v[52:55], v[140:143], v[172:175], v[52:55]
	v_mfma_f32_16x16x32_bf16 v[48:51], v[156:159], v[172:175], v[48:51]
	v_mfma_f32_16x16x32_bf16 v[28:31], v[140:143], v[180:183], v[28:31]
	v_mfma_f32_16x16x32_bf16 v[24:27], v[156:159], v[180:183], v[24:27]
	v_mfma_f32_16x16x32_bf16 v[16:19], v[140:143], v[188:191], v[16:19]
	v_mfma_f32_16x16x32_bf16 v[8:11], v[156:159], v[188:191], v[8:11]
	v_mfma_f32_16x16x32_bf16 v[60:63], v[152:155], v[168:171], v[60:63]
	v_mfma_f32_16x16x32_bf16 v[56:59], v[160:163], v[168:171], v[56:59]
	v_mfma_f32_16x16x32_bf16 v[52:55], v[152:155], v[176:179], v[52:55]
	v_mfma_f32_16x16x32_bf16 v[48:51], v[160:163], v[176:179], v[48:51]
	v_mfma_f32_16x16x32_bf16 v[28:31], v[152:155], v[184:187], v[28:31]
	v_mfma_f32_16x16x32_bf16 v[24:27], v[160:163], v[184:187], v[24:27]
	v_mfma_f32_16x16x32_bf16 v[16:19], v[152:155], v[192:195], v[16:19]
	v_mfma_f32_16x16x32_bf16 v[8:11], v[160:163], v[192:195], v[8:11]
	s_barrier
	s_add_u32 s2, s12, 0xb0080
	s_addc_u32 s3, s13, 0
	s_add_i32 s12, s14, s22
	v_lshl_add_u64 v[140:141], s[2:3], 0, v[128:129]
	s_mov_b32 m0, s12
	s_nop 0
	global_load_lds_dwordx4 v[140:141], off
	v_lshl_add_u64 v[140:141], s[2:3], 0, v[130:131]
	s_add_i32 m0, s12, 0x2000
	s_nop 0
	global_load_lds_dwordx4 v[140:141], off
	s_waitcnt vmcnt(6)
	s_barrier
	v_mfma_f32_16x16x32_bf16 v[44:47], v[196:199], v[164:167], v[44:47]
	v_mfma_f32_16x16x32_bf16 v[40:43], v[204:207], v[164:167], v[40:43]
	v_mfma_f32_16x16x32_bf16 v[36:39], v[196:199], v[172:175], v[36:39]
	v_mfma_f32_16x16x32_bf16 v[32:35], v[204:207], v[172:175], v[32:35]
	v_mfma_f32_16x16x32_bf16 v[20:23], v[196:199], v[180:183], v[20:23]
	v_mfma_f32_16x16x32_bf16 v[12:15], v[204:207], v[180:183], v[12:15]
	v_mfma_f32_16x16x32_bf16 v[4:7], v[196:199], v[188:191], v[4:7]
	v_mfma_f32_16x16x32_bf16 v[0:3], v[204:207], v[188:191], v[0:3]
	v_mfma_f32_16x16x32_bf16 v[44:47], v[200:203], v[168:171], v[44:47]
	v_mfma_f32_16x16x32_bf16 v[40:43], v[208:211], v[168:171], v[40:43]
	v_mfma_f32_16x16x32_bf16 v[36:39], v[200:203], v[176:179], v[36:39]
	v_mfma_f32_16x16x32_bf16 v[32:35], v[208:211], v[176:179], v[32:35]
	v_mfma_f32_16x16x32_bf16 v[20:23], v[200:203], v[184:187], v[20:23]
	v_mfma_f32_16x16x32_bf16 v[12:15], v[208:211], v[184:187], v[12:15]
	v_mfma_f32_16x16x32_bf16 v[4:7], v[200:203], v[192:195], v[4:7]
	v_mfma_f32_16x16x32_bf16 v[0:3], v[208:211], v[192:195], v[0:3]
	s_add_i32 s39, s39, 2
	s_add_u32 s37, s37, 0x100
	s_addc_u32 s38, s38, 0
	s_cmp_gt_u32 s39, 41
	s_mov_b64 s[2:3], s[10:11]
	s_barrier
	s_cbranch_scc0 .LBB0_888
	s_cmpk_gt_u32 s16, 0xff
	s_cbranch_scc1 .Lepi0_ffnout
	s_barrier
.Lepi0_ffnout:
	v_lshl_or_b32 v140, s36, 8, v148
	v_lshl_add_u32 v144, s35, 8, v146
	v_ashrrev_i32_e32 v141, 31, v140
	v_lshlrev_b64 v[140:141], 2, v[140:141]
	v_ashrrev_i32_e32 v145, 31, v144
	v_lshl_add_u64 v[142:143], s[78:79], 0, v[140:141]
	v_lshlrev_b64 v[184:185], 12, v[144:145]
	v_lshl_add_u64 v[164:165], v[142:143], 0, v[184:185]
	v_or_b32_e32 v168, 16, v144
	global_load_dwordx4 v[152:155], v[164:165], off offset:16
	global_load_dwordx4 v[156:159], v[164:165], off
	global_load_dwordx4 v[160:163], v[164:165], off offset:144
	s_nop 0
	global_load_dwordx4 v[164:167], v[164:165], off offset:128
	v_ashrrev_i32_e32 v169, 31, v168
	v_lshlrev_b64 v[186:187], 12, v[168:169]
	v_lshl_add_u64 v[180:181], v[142:143], 0, v[186:187]
	global_load_dwordx4 v[168:171], v[180:181], off offset:16
	global_load_dwordx4 v[172:175], v[180:181], off
	global_load_dwordx4 v[176:179], v[180:181], off offset:144
	s_nop 0
	global_load_dwordx4 v[180:183], v[180:181], off offset:128
	s_and_b64 vcc, exec, s[0:1]
	s_mov_b32 s36, s34
	s_mov_b32 s35, s33
	s_mov_b64 s[10:11], s[4:5]
	s_mov_b64 s[2:3], s[6:7]
	s_waitcnt vmcnt(0)
	v_pk_add_f32 v[120:121], v[120:121], v[152:153]
	v_lshl_add_u64 v[152:153], s[78:79], 0, v[184:185]
	v_pk_add_f32 v[126:127], v[126:127], v[158:159]
	v_pk_add_f32 v[124:125], v[124:125], v[156:157]
	v_pk_add_f32 v[108:109], v[108:109], v[164:165]
	v_lshl_add_u64 v[152:153], v[152:153], 0, v[140:141]
	v_pk_add_f32 v[122:123], v[122:123], v[154:155]
	v_pk_add_f32 v[110:111], v[110:111], v[166:167]
	v_pk_add_f32 v[106:107], v[106:107], v[162:163]
	v_pk_add_f32 v[104:105], v[104:105], v[160:161]
	global_store_dwordx4 v[152:153], v[124:127], off nt
	global_store_dwordx4 v[152:153], v[120:123], off offset:16 nt
	global_store_dwordx4 v[152:153], v[108:111], off offset:128 nt
	global_store_dwordx4 v[152:153], v[104:107], off offset:144 nt
	v_pk_add_f32 v[96:97], v[96:97], v[176:177]
	v_pk_add_f32 v[108:109], v[112:113], v[168:169]
	v_lshl_add_u64 v[112:113], s[78:79], 0, v[186:187]
	v_pk_add_f32 v[106:107], v[118:119], v[174:175]
	v_pk_add_f32 v[104:105], v[116:117], v[172:173]
	v_lshl_add_u64 v[112:113], v[112:113], 0, v[140:141]
	v_pk_add_f32 v[110:111], v[114:115], v[170:171]
	v_pk_add_f32 v[102:103], v[102:103], v[182:183]
	v_pk_add_f32 v[100:101], v[100:101], v[180:181]
	v_pk_add_f32 v[98:99], v[98:99], v[178:179]
	global_store_dwordx4 v[112:113], v[104:107], off nt
	global_store_dwordx4 v[112:113], v[108:111], off offset:16 nt
	global_store_dwordx4 v[112:113], v[100:103], off offset:128 nt
	global_store_dwordx4 v[112:113], v[96:99], off offset:144 nt
	v_or_b32_e32 v112, 48, v144
	v_ashrrev_i32_e32 v113, 31, v112
	v_or_b32_e32 v96, 32, v144
	v_ashrrev_i32_e32 v97, 31, v96
	v_lshlrev_b64 v[152:153], 12, v[96:97]
	v_lshl_add_u64 v[108:109], v[142:143], 0, v[152:153]
	global_load_dwordx4 v[96:99], v[108:109], off offset:16
	global_load_dwordx4 v[100:103], v[108:109], off
	global_load_dwordx4 v[104:107], v[108:109], off offset:144
	s_nop 0
	global_load_dwordx4 v[108:111], v[108:109], off offset:128
	v_lshlrev_b64 v[154:155], 12, v[112:113]
	v_lshl_add_u64 v[124:125], v[142:143], 0, v[154:155]
	global_load_dwordx4 v[112:115], v[124:125], off offset:16
	global_load_dwordx4 v[116:119], v[124:125], off
	global_load_dwordx4 v[120:123], v[124:125], off offset:144
	s_nop 0
	global_load_dwordx4 v[124:127], v[124:125], off offset:128
	s_waitcnt vmcnt(0)
	v_pk_add_f32 v[88:89], v[88:89], v[96:97]
	v_lshl_add_u64 v[96:97], s[78:79], 0, v[152:153]
	v_pk_add_f32 v[94:95], v[94:95], v[102:103]
	v_pk_add_f32 v[92:93], v[92:93], v[100:101]
	v_pk_add_f32 v[76:77], v[76:77], v[108:109]
	v_lshl_add_u64 v[96:97], v[96:97], 0, v[140:141]
	v_pk_add_f32 v[90:91], v[90:91], v[98:99]
	v_pk_add_f32 v[78:79], v[78:79], v[110:111]
	v_pk_add_f32 v[74:75], v[74:75], v[106:107]
	v_pk_add_f32 v[72:73], v[72:73], v[104:105]
	global_store_dwordx4 v[96:97], v[92:95], off nt
	global_store_dwordx4 v[96:97], v[88:91], off offset:16 nt
	global_store_dwordx4 v[96:97], v[76:79], off offset:128 nt
	global_store_dwordx4 v[96:97], v[72:75], off offset:144 nt
	v_pk_add_f32 v[64:65], v[64:65], v[120:121]
	v_pk_add_f32 v[76:77], v[80:81], v[112:113]
	v_lshl_add_u64 v[80:81], s[78:79], 0, v[154:155]
	v_pk_add_f32 v[74:75], v[86:87], v[118:119]
	v_pk_add_f32 v[72:73], v[84:85], v[116:117]
	v_lshl_add_u64 v[80:81], v[80:81], 0, v[140:141]
	v_pk_add_f32 v[78:79], v[82:83], v[114:115]
	v_pk_add_f32 v[70:71], v[70:71], v[126:127]
	v_pk_add_f32 v[68:69], v[68:69], v[124:125]
	v_pk_add_f32 v[66:67], v[66:67], v[122:123]
	global_store_dwordx4 v[80:81], v[72:75], off nt
	global_store_dwordx4 v[80:81], v[76:79], off offset:16 nt
	global_store_dwordx4 v[80:81], v[68:71], off offset:128 nt
	global_store_dwordx4 v[80:81], v[64:67], off offset:144 nt
	s_nop 1
	v_add_u32_e32 v64, 0x80, v144
	v_ashrrev_i32_e32 v65, 31, v64
	v_lshlrev_b64 v[96:97], 12, v[64:65]
	v_lshl_add_u64 v[80:81], v[142:143], 0, v[96:97]
	global_load_dwordx4 v[64:67], v[80:81], off offset:16
	global_load_dwordx4 v[68:71], v[80:81], off
	global_load_dwordx4 v[72:75], v[80:81], off offset:144
	global_load_dwordx4 v[76:79], v[80:81], off offset:128
	v_add_u32_e32 v80, 0x90, v144
	v_ashrrev_i32_e32 v81, 31, v80
	v_lshlrev_b64 v[98:99], 12, v[80:81]
	v_lshl_add_u64 v[100:101], v[142:143], 0, v[98:99]
	global_load_dwordx4 v[80:83], v[100:101], off offset:16
	global_load_dwordx4 v[84:87], v[100:101], off
	global_load_dwordx4 v[88:91], v[100:101], off offset:144
	global_load_dwordx4 v[92:95], v[100:101], off offset:128
	s_waitcnt vmcnt(0)
	v_pk_add_f32 v[56:57], v[56:57], v[64:65]
	v_lshl_add_u64 v[64:65], s[78:79], 0, v[96:97]
	v_pk_add_f32 v[62:63], v[62:63], v[70:71]
	v_pk_add_f32 v[60:61], v[60:61], v[68:69]
	v_pk_add_f32 v[44:45], v[44:45], v[76:77]
	v_lshl_add_u64 v[64:65], v[64:65], 0, v[140:141]
	v_pk_add_f32 v[58:59], v[58:59], v[66:67]
	v_pk_add_f32 v[46:47], v[46:47], v[78:79]
	v_pk_add_f32 v[42:43], v[42:43], v[74:75]
	v_pk_add_f32 v[40:41], v[40:41], v[72:73]
	global_store_dwordx4 v[64:65], v[60:63], off nt
	global_store_dwordx4 v[64:65], v[56:59], off offset:16 nt
	global_store_dwordx4 v[64:65], v[44:47], off offset:128 nt
	global_store_dwordx4 v[64:65], v[40:43], off offset:144 nt
	v_pk_add_f32 v[32:33], v[32:33], v[88:89]
	v_pk_add_f32 v[44:45], v[48:49], v[80:81]
	v_lshl_add_u64 v[48:49], s[78:79], 0, v[98:99]
	v_pk_add_f32 v[42:43], v[54:55], v[86:87]
	v_pk_add_f32 v[40:41], v[52:53], v[84:85]
	v_lshl_add_u64 v[48:49], v[48:49], 0, v[140:141]
	v_pk_add_f32 v[46:47], v[50:51], v[82:83]
	v_pk_add_f32 v[38:39], v[38:39], v[94:95]
	v_pk_add_f32 v[36:37], v[36:37], v[92:93]
	v_pk_add_f32 v[34:35], v[34:35], v[90:91]
	global_store_dwordx4 v[48:49], v[40:43], off nt
	global_store_dwordx4 v[48:49], v[44:47], off offset:16 nt
	global_store_dwordx4 v[48:49], v[36:39], off offset:128 nt
	global_store_dwordx4 v[48:49], v[32:35], off offset:144 nt
	s_nop 1
	v_add_u32_e32 v32, 0xa0, v144
	v_ashrrev_i32_e32 v33, 31, v32
	v_lshlrev_b64 v[60:61], 12, v[32:33]
	v_lshl_add_u64 v[48:49], v[142:143], 0, v[60:61]
	global_load_dwordx4 v[40:43], v[48:49], off offset:16
	global_load_dwordx4 v[44:47], v[48:49], off
	global_load_dwordx4 v[32:35], v[48:49], off offset:144
	global_load_dwordx4 v[36:39], v[48:49], off offset:128
	v_add_u32_e32 v48, 0xb0, v144
	v_ashrrev_i32_e32 v49, 31, v48
	v_lshlrev_b64 v[62:63], 12, v[48:49]
	v_lshl_add_u64 v[68:69], v[142:143], 0, v[62:63]
	global_load_dwordx4 v[48:51], v[68:69], off offset:16
	global_load_dwordx4 v[56:59], v[68:69], off
	global_load_dwordx4 v[52:55], v[68:69], off offset:144
	global_load_dwordx4 v[64:67], v[68:69], off offset:128
	s_waitcnt vmcnt(0)
	v_pk_add_f32 v[26:27], v[26:27], v[42:43]
	v_pk_add_f32 v[30:31], v[30:31], v[46:47]
	v_pk_add_f32 v[12:13], v[12:13], v[32:33]
	v_lshl_add_u64 v[32:33], s[78:79], 0, v[60:61]
	v_pk_add_f32 v[28:29], v[28:29], v[44:45]
	v_lshl_add_u64 v[32:33], v[32:33], 0, v[140:141]
	v_pk_add_f32 v[24:25], v[24:25], v[40:41]
	v_pk_add_f32 v[22:23], v[22:23], v[38:39]
	v_pk_add_f32 v[20:21], v[20:21], v[36:37]
	v_pk_add_f32 v[14:15], v[14:15], v[34:35]
	global_store_dwordx4 v[32:33], v[28:31], off nt
	global_store_dwordx4 v[32:33], v[24:27], off offset:16 nt
	global_store_dwordx4 v[32:33], v[20:23], off offset:128 nt
	global_store_dwordx4 v[32:33], v[12:15], off offset:144 nt
	v_pk_add_f32 v[10:11], v[10:11], v[50:51]
	v_pk_add_f32 v[8:9], v[8:9], v[48:49]
	v_pk_add_f32 v[12:13], v[16:17], v[56:57]
	v_lshl_add_u64 v[16:17], s[78:79], 0, v[62:63]
	v_pk_add_f32 v[14:15], v[18:19], v[58:59]
	v_lshl_add_u64 v[16:17], v[16:17], 0, v[140:141]
	v_pk_add_f32 v[6:7], v[6:7], v[66:67]
	v_pk_add_f32 v[4:5], v[4:5], v[64:65]
	v_pk_add_f32 v[2:3], v[2:3], v[54:55]
	v_pk_add_f32 v[0:1], v[0:1], v[52:53]
	global_store_dwordx4 v[16:17], v[12:15], off nt
	global_store_dwordx4 v[16:17], v[8:11], off offset:16 nt
	global_store_dwordx4 v[16:17], v[4:7], off offset:128 nt
	global_store_dwordx4 v[16:17], v[0:3], off offset:144 nt
	s_cmpk_gt_u32 s16, 0xff
	s_cbranch_scc0 .Lepi1_ffnout
	s_barrier
.Lepi1_ffnout:
	s_cbranch_vccz .LBB0_877
	s_waitcnt vmcnt(0)
	s_cmpk_gt_u32 s16, 0xff
	s_cbranch_scc1 .LBB0_892
	s_barrier
